# V phase: fourth gather buffer in AGPRs (three units of lead), 16 LDS record slots
# speedup vs baseline: 1.0023x; 1.0023x over previous
; #define P5_LOAD(A, TAB, j0)                                                                \
;   _Pragma("unroll") for (int q = 0; q < 16; q++) {                                         \
;     A[q] = ((const uint4*)((TAB) + (size_t)widx[(j0) + q] * 1024))[lane];                  \
;   }
; __device__ __forceinline__ void phase5(const Params& p, char* smem, const bool store_x = true) {
;     ...
; #pragma unroll 1
;     for (int j0 = 0; j0 < 128; j0 += 32) {
;       P5_LOAD(A1, EV, j0 + 16)
;       P5_COMPUTE_V(A0, j0)
;       if (j0 + 32 < 128) { P5_LOAD(A0, EV, j0 + 32) }
;       P5_COMPUTE_V(A1, j0 + 16)
;     }
.Lp5v_start:
	v_mbcnt_lo_u32_b32 v0, -1, 0
	v_mbcnt_hi_u32_b32 v0, -1, v0
	v_accvgpr_read_b32 v4, a129
	s_and_b32 s0, s96, 7
	s_lshr_b32 s1, s96, 3
	v_and_b32_e32 v1, 7, v0
	v_lshrrev_b32_e32 v2, 3, v0
	v_lshlrev_b32_e32 v3, 1, v2
	v_lshl_add_u32 v3, v1, 4, v3
	v_lshlrev_b32_e32 v3, 2, v3
	v_lshlrev_b32_e32 v1, 4, v1
	v_lshlrev_b32_e32 v2, 6, v2
	v_readfirstlane_b32 s8, v4
	s_lshl_b32 s17, s8, 14
	v_add_u32_e32 v2, s17, v2
	s_lshl_b32 s10, s1, 2
	s_add_u32 s8, s8, s10
	s_lshr_b32 s9, s82, 1
	s_lshl_b32 s10, s0, 21
	s_add_u32 s2, s80, 0xbf35000
	s_addc_u32 s3, s81, 0
	s_add_u32 s2, s2, s10
	s_addc_u32 s3, s3, 0
	s_add_u32 s4, s80, 0x3bb5000
	s_addc_u32 s5, s81, 0
	s_lshl_b32 s10, s0, 9
	s_add_u32 s6, s78, s10
	s_addc_u32 s7, s79, 0
	s_movk_i32 s13, 0x41ff
	s_mov_b32 s14, 0xff00ff00
	s_mov_b32 s15, 0xff00ff00
	s_mov_b32 s16, 0
	s_mov_b32 s19, 0
	v_lshlrev_b32_e32 v9, 4, v0
	v_mov_b32_e32 v59, s5
	v_add_co_u32_e32 v58, vcc, s4, v9
	s_nop 1
	v_addc_co_u32_e32 v59, vcc, 0, v59, vcc
	s_mul_i32 s20, s9, 1
	s_mul_i32 s21, s9, 2
	s_mul_i32 s22, s9, 3
	s_mul_i32 s23, s9, 4
	s_mul_i32 s24, s9, 5
	s_mul_i32 s25, s9, 6
	s_mul_i32 s26, s9, 7
	s_mul_i32 s27, s9, 8
	s_mul_i32 s28, s9, 9
	s_mul_i32 s29, s9, 10
	s_mul_i32 s33, s9, 11
	s_min_u32 s10, s8, s13
	s_lshl_b32 s18, s10, 10
	s_add_u32 s11, s16, 0
	s_and_b32 s11, s11, 15
	s_lshl_b32 s11, s11, 10
	s_add_u32 s11, s11, s17
	s_mov_b32 m0, s11
	v_lshl_add_u64 v[4:5], v[58:59], 0, s[18:19]
	global_load_lds_dwordx4 v[4:5], off
	s_add_u32 s10, s8, s20
	s_min_u32 s10, s10, s13
	s_lshl_b32 s18, s10, 10
	s_add_u32 s11, s16, 1
	s_and_b32 s11, s11, 15
	s_lshl_b32 s11, s11, 10
	s_add_u32 s11, s11, s17
	s_mov_b32 m0, s11
	v_lshl_add_u64 v[4:5], v[58:59], 0, s[18:19]
	global_load_lds_dwordx4 v[4:5], off
	s_add_u32 s10, s8, s21
	s_min_u32 s10, s10, s13
	s_lshl_b32 s18, s10, 10
	s_add_u32 s11, s16, 2
	s_and_b32 s11, s11, 15
	s_lshl_b32 s11, s11, 10
	s_add_u32 s11, s11, s17
	s_mov_b32 m0, s11
	v_lshl_add_u64 v[4:5], v[58:59], 0, s[18:19]
	global_load_lds_dwordx4 v[4:5], off
	s_add_u32 s10, s8, s22
	s_min_u32 s10, s10, s13
	s_lshl_b32 s18, s10, 10
	s_add_u32 s11, s16, 3
	s_and_b32 s11, s11, 15
	s_lshl_b32 s11, s11, 10
	s_add_u32 s11, s11, s17
	s_mov_b32 m0, s11
	v_lshl_add_u64 v[4:5], v[58:59], 0, s[18:19]
	global_load_lds_dwordx4 v[4:5], off
	s_add_u32 s10, s8, s23
	s_min_u32 s10, s10, s13
	s_lshl_b32 s18, s10, 10
	s_add_u32 s11, s16, 4
	s_and_b32 s11, s11, 15
	s_lshl_b32 s11, s11, 10
	s_add_u32 s11, s11, s17
	s_mov_b32 m0, s11
	v_lshl_add_u64 v[4:5], v[58:59], 0, s[18:19]
	global_load_lds_dwordx4 v[4:5], off
	s_add_u32 s10, s8, s24
	s_min_u32 s10, s10, s13
	s_lshl_b32 s18, s10, 10
	s_add_u32 s11, s16, 5
	s_and_b32 s11, s11, 15
	s_lshl_b32 s11, s11, 10
	s_add_u32 s11, s11, s17
	s_mov_b32 m0, s11
	v_lshl_add_u64 v[4:5], v[58:59], 0, s[18:19]
	global_load_lds_dwordx4 v[4:5], off
	s_add_u32 s10, s8, s25
	s_min_u32 s10, s10, s13
	s_lshl_b32 s18, s10, 10
	s_add_u32 s11, s16, 6
	s_and_b32 s11, s11, 15
	s_lshl_b32 s11, s11, 10
	s_add_u32 s11, s11, s17
	s_mov_b32 m0, s11
	v_lshl_add_u64 v[4:5], v[58:59], 0, s[18:19]
	global_load_lds_dwordx4 v[4:5], off
	s_add_u32 s10, s8, s26
	s_min_u32 s10, s10, s13
	s_lshl_b32 s18, s10, 10
	s_add_u32 s11, s16, 7
	s_and_b32 s11, s11, 15
	s_lshl_b32 s11, s11, 10
	s_add_u32 s11, s11, s17
	s_mov_b32 m0, s11
	v_lshl_add_u64 v[4:5], v[58:59], 0, s[18:19]
	global_load_lds_dwordx4 v[4:5], off
	s_waitcnt vmcnt(0)
	s_add_u32 s11, s16, 0
	s_and_b32 s11, s11, 15
	s_lshl_b32 s11, s11, 10
	v_add_u32_e32 v8, s11, v2
	ds_read_b128 v[10:13], v8 offset:0
	ds_read_b128 v[14:17], v8 offset:16
	ds_read_b128 v[18:21], v8 offset:32
	ds_read_b128 v[22:25], v8 offset:48
	s_min_u32 s10, s8, s13
	s_lshl_b32 s11, s10, 12
	v_add_u32_e32 v6, s11, v3
	global_load_dwordx2 v[50:51], v6, s[6:7]
	s_waitcnt lgkmcnt(0)
	v_add_u32_e32 v10, v10, v1
	global_load_dwordx4 v[60:63], v10, s[2:3]
	v_add_u32_e32 v11, v11, v1
	global_load_dwordx4 v[64:67], v11, s[2:3]
	v_add_u32_e32 v12, v12, v1
	global_load_dwordx4 v[68:71], v12, s[2:3]
	v_add_u32_e32 v13, v13, v1
	global_load_dwordx4 v[72:75], v13, s[2:3]
	v_add_u32_e32 v14, v14, v1
	global_load_dwordx4 v[76:79], v14, s[2:3]
	v_add_u32_e32 v15, v15, v1
	global_load_dwordx4 v[80:83], v15, s[2:3]
	v_add_u32_e32 v16, v16, v1
	global_load_dwordx4 v[84:87], v16, s[2:3]
	v_add_u32_e32 v17, v17, v1
	global_load_dwordx4 v[88:91], v17, s[2:3]
	v_add_u32_e32 v18, v18, v1
	global_load_dwordx4 v[92:95], v18, s[2:3]
	v_add_u32_e32 v19, v19, v1
	global_load_dwordx4 v[96:99], v19, s[2:3]
	v_add_u32_e32 v20, v20, v1
	global_load_dwordx4 v[100:103], v20, s[2:3]
	v_add_u32_e32 v21, v21, v1
	global_load_dwordx4 v[104:107], v21, s[2:3]
	v_add_u32_e32 v22, v22, v1
	global_load_dwordx4 v[108:111], v22, s[2:3]
	v_add_u32_e32 v23, v23, v1
	global_load_dwordx4 v[112:115], v23, s[2:3]
	v_add_u32_e32 v24, v24, v1
	global_load_dwordx4 v[116:119], v24, s[2:3]
	v_add_u32_e32 v25, v25, v1
	global_load_dwordx4 v[120:123], v25, s[2:3]
	global_load_dword v252, v6, s[6:7]
	global_load_dword v252, v6, s[6:7]
	global_load_dword v252, v6, s[6:7]
	s_add_u32 s11, s16, 1
	s_and_b32 s11, s11, 15
	s_lshl_b32 s11, s11, 10
	v_add_u32_e32 v8, s11, v2
	ds_read_b128 v[10:13], v8 offset:0
	ds_read_b128 v[14:17], v8 offset:16
	ds_read_b128 v[18:21], v8 offset:32
	ds_read_b128 v[22:25], v8 offset:48
	s_add_u32 s10, s8, s20
	s_min_u32 s10, s10, s13
	s_lshl_b32 s11, s10, 12
	v_add_u32_e32 v6, s11, v3
	global_load_dwordx2 v[52:53], v6, s[6:7]
	s_waitcnt lgkmcnt(0)
; #define P5_LOAD(A, TAB, j0)                                                                \
;   _Pragma("unroll") for (int q = 0; q < 16; q++) {                                         \
;     A[q] = ((const uint4*)((TAB) + (size_t)widx[(j0) + q] * 1024))[lane];                  \
;   }
; __device__ __forceinline__ void phase5(const Params& p, char* smem, const bool store_x = true) {
;     ...
; #pragma unroll 1
;     for (int j0 = 0; j0 < 128; j0 += 32) {
;       P5_LOAD(A1, EV, j0 + 16)
;       P5_COMPUTE_V(A0, j0)
;       if (j0 + 32 < 128) { P5_LOAD(A0, EV, j0 + 32) }
;       P5_COMPUTE_V(A1, j0 + 16)
;     }
	v_add_u32_e32 v10, v10, v1
	global_load_dwordx4 v[124:127], v10, s[2:3]
	v_add_u32_e32 v11, v11, v1
	global_load_dwordx4 v[128:131], v11, s[2:3]
	v_add_u32_e32 v12, v12, v1
	global_load_dwordx4 v[132:135], v12, s[2:3]
	v_add_u32_e32 v13, v13, v1
	global_load_dwordx4 v[136:139], v13, s[2:3]
	v_add_u32_e32 v14, v14, v1
	global_load_dwordx4 v[140:143], v14, s[2:3]
	v_add_u32_e32 v15, v15, v1
	global_load_dwordx4 v[144:147], v15, s[2:3]
	v_add_u32_e32 v16, v16, v1
	global_load_dwordx4 v[148:151], v16, s[2:3]
	v_add_u32_e32 v17, v17, v1
	global_load_dwordx4 v[152:155], v17, s[2:3]
	v_add_u32_e32 v18, v18, v1
	global_load_dwordx4 v[156:159], v18, s[2:3]
	v_add_u32_e32 v19, v19, v1
	global_load_dwordx4 v[160:163], v19, s[2:3]
	v_add_u32_e32 v20, v20, v1
	global_load_dwordx4 v[164:167], v20, s[2:3]
	v_add_u32_e32 v21, v21, v1
	global_load_dwordx4 v[168:171], v21, s[2:3]
	v_add_u32_e32 v22, v22, v1
	global_load_dwordx4 v[172:175], v22, s[2:3]
	v_add_u32_e32 v23, v23, v1
	global_load_dwordx4 v[176:179], v23, s[2:3]
	v_add_u32_e32 v24, v24, v1
	global_load_dwordx4 v[180:183], v24, s[2:3]
	v_add_u32_e32 v25, v25, v1
	global_load_dwordx4 v[184:187], v25, s[2:3]
	global_load_dword v252, v6, s[6:7]
	global_load_dword v252, v6, s[6:7]
	global_load_dword v252, v6, s[6:7]
	s_add_u32 s11, s16, 2
	s_and_b32 s11, s11, 15
	s_lshl_b32 s11, s11, 10
	v_add_u32_e32 v8, s11, v2
	ds_read_b128 v[10:13], v8 offset:0
	ds_read_b128 v[14:17], v8 offset:16
	ds_read_b128 v[18:21], v8 offset:32
	ds_read_b128 v[22:25], v8 offset:48
	s_add_u32 s10, s8, s21
	s_min_u32 s10, s10, s13
	s_lshl_b32 s11, s10, 12
	v_add_u32_e32 v6, s11, v3
	global_load_dwordx2 v[54:55], v6, s[6:7]
	s_waitcnt lgkmcnt(0)
	v_add_u32_e32 v10, v10, v1
	global_load_dwordx4 v[188:191], v10, s[2:3]
	v_add_u32_e32 v11, v11, v1
	global_load_dwordx4 v[192:195], v11, s[2:3]
	v_add_u32_e32 v12, v12, v1
	global_load_dwordx4 v[196:199], v12, s[2:3]
	v_add_u32_e32 v13, v13, v1
	global_load_dwordx4 v[200:203], v13, s[2:3]
	v_add_u32_e32 v14, v14, v1
	global_load_dwordx4 v[204:207], v14, s[2:3]
	v_add_u32_e32 v15, v15, v1
	global_load_dwordx4 v[208:211], v15, s[2:3]
	v_add_u32_e32 v16, v16, v1
	global_load_dwordx4 v[212:215], v16, s[2:3]
	v_add_u32_e32 v17, v17, v1
	global_load_dwordx4 v[216:219], v17, s[2:3]
	v_add_u32_e32 v18, v18, v1
	global_load_dwordx4 v[220:223], v18, s[2:3]
	v_add_u32_e32 v19, v19, v1
	global_load_dwordx4 v[224:227], v19, s[2:3]
	v_add_u32_e32 v20, v20, v1
	global_load_dwordx4 v[228:231], v20, s[2:3]
	v_add_u32_e32 v21, v21, v1
	global_load_dwordx4 v[232:235], v21, s[2:3]
	v_add_u32_e32 v22, v22, v1
	global_load_dwordx4 v[236:239], v22, s[2:3]
	v_add_u32_e32 v23, v23, v1
	global_load_dwordx4 v[240:243], v23, s[2:3]
	v_add_u32_e32 v24, v24, v1
	global_load_dwordx4 v[244:247], v24, s[2:3]
	v_add_u32_e32 v25, v25, v1
	global_load_dwordx4 v[248:251], v25, s[2:3]
	global_load_dword v252, v6, s[6:7]
	global_load_dword v252, v6, s[6:7]
.Lp5v_loop:
	s_add_u32 s10, s8, s27
	s_min_u32 s10, s10, s13
	s_lshl_b32 s18, s10, 10
	s_add_u32 s11, s16, 8
	s_and_b32 s11, s11, 15
	s_lshl_b32 s11, s11, 10
	s_add_u32 s11, s11, s17
	s_mov_b32 m0, s11
	v_lshl_add_u64 v[4:5], v[58:59], 0, s[18:19]
	global_load_lds_dwordx4 v[4:5], off
	s_add_u32 s11, s16, 3
	s_and_b32 s11, s11, 15
	s_lshl_b32 s11, s11, 10
	v_add_u32_e32 v8, s11, v2
	ds_read_b128 v[10:13], v8 offset:0
	ds_read_b128 v[14:17], v8 offset:16
	ds_read_b128 v[18:21], v8 offset:32
	ds_read_b128 v[22:25], v8 offset:48
	s_add_u32 s10, s8, s22
	s_min_u32 s10, s10, s13
	s_lshl_b32 s11, s10, 12
	v_add_u32_e32 v6, s11, v3
	global_load_dwordx2 v[56:57], v6, s[6:7]
	s_waitcnt lgkmcnt(0)
	v_add_u32_e32 v10, v10, v1
	global_load_dwordx4 a[0:3], v10, s[2:3]
	v_add_u32_e32 v11, v11, v1
	global_load_dwordx4 a[4:7], v11, s[2:3]
	v_add_u32_e32 v12, v12, v1
	global_load_dwordx4 a[8:11], v12, s[2:3]
	v_add_u32_e32 v13, v13, v1
	global_load_dwordx4 a[12:15], v13, s[2:3]
	v_add_u32_e32 v14, v14, v1
	global_load_dwordx4 a[16:19], v14, s[2:3]
	v_add_u32_e32 v15, v15, v1
	global_load_dwordx4 a[20:23], v15, s[2:3]
	v_add_u32_e32 v16, v16, v1
	global_load_dwordx4 a[24:27], v16, s[2:3]
	v_add_u32_e32 v17, v17, v1
	global_load_dwordx4 a[28:31], v17, s[2:3]
	v_add_u32_e32 v18, v18, v1
	global_load_dwordx4 a[32:35], v18, s[2:3]
	v_add_u32_e32 v19, v19, v1
	global_load_dwordx4 a[36:39], v19, s[2:3]
	v_add_u32_e32 v20, v20, v1
	global_load_dwordx4 a[40:43], v20, s[2:3]
	v_add_u32_e32 v21, v21, v1
	global_load_dwordx4 a[44:47], v21, s[2:3]
	v_add_u32_e32 v22, v22, v1
	global_load_dwordx4 a[48:51], v22, s[2:3]
	v_add_u32_e32 v23, v23, v1
	global_load_dwordx4 a[52:55], v23, s[2:3]
	v_add_u32_e32 v24, v24, v1
	global_load_dwordx4 a[56:59], v24, s[2:3]
	v_add_u32_e32 v25, v25, v1
	global_load_dwordx4 a[60:63], v25, s[2:3]
	s_add_u32 s11, s16, 0
	s_and_b32 s11, s11, 15
	s_lshl_b32 s11, s11, 10
	v_add_u32_e32 v8, s11, v2
	ds_read_b128 v[10:13], v8 offset:512
	ds_read_b128 v[14:17], v8 offset:528
	ds_read_b128 v[18:21], v8 offset:544
	ds_read_b128 v[22:25], v8 offset:560
	s_mov_b32 s12, s8
	s_waitcnt vmcnt(60) lgkmcnt(0)
	s_cmp_lt_u32 s12, 0x4200
	s_cbranch_scc0 .Lp5v_skip0
	v_cvt_pk_f32_fp8_e32 v[42:43], v60
	v_cvt_pk_f32_fp8_sdwa v[44:45], v60 src0_sel:WORD_1
	v_pk_mul_f32 v[26:27], v[42:43], v[10:11] op_sel_hi:[1,0]
	v_pk_mul_f32 v[28:29], v[44:45], v[10:11] op_sel_hi:[1,0]
	v_cvt_pk_f32_fp8_e32 v[46:47], v61
	v_cvt_pk_f32_fp8_sdwa v[48:49], v61 src0_sel:WORD_1
	v_pk_mul_f32 v[30:31], v[46:47], v[10:11] op_sel_hi:[1,0]
	v_pk_mul_f32 v[32:33], v[48:49], v[10:11] op_sel_hi:[1,0]
	v_cvt_pk_f32_fp8_e32 v[42:43], v62
	v_cvt_pk_f32_fp8_sdwa v[44:45], v62 src0_sel:WORD_1
	v_pk_mul_f32 v[34:35], v[42:43], v[10:11] op_sel_hi:[1,0]
	v_pk_mul_f32 v[36:37], v[44:45], v[10:11] op_sel_hi:[1,0]
	v_cvt_pk_f32_fp8_e32 v[46:47], v63
	v_cvt_pk_f32_fp8_sdwa v[48:49], v63 src0_sel:WORD_1
	v_pk_mul_f32 v[38:39], v[46:47], v[10:11] op_sel_hi:[1,0]
	v_pk_mul_f32 v[40:41], v[48:49], v[10:11] op_sel_hi:[1,0]
	v_cvt_pk_f32_fp8_e32 v[42:43], v64
	v_cvt_pk_f32_fp8_sdwa v[44:45], v64 src0_sel:WORD_1
	v_pk_fma_f32 v[26:27], v[42:43], v[10:11], v[26:27] op_sel:[0,1,0] op_sel_hi:[1,1,1]
	v_pk_fma_f32 v[28:29], v[44:45], v[10:11], v[28:29] op_sel:[0,1,0] op_sel_hi:[1,1,1]
	v_cvt_pk_f32_fp8_e32 v[46:47], v65
	v_cvt_pk_f32_fp8_sdwa v[48:49], v65 src0_sel:WORD_1
	v_pk_fma_f32 v[30:31], v[46:47], v[10:11], v[30:31] op_sel:[0,1,0] op_sel_hi:[1,1,1]
	v_pk_fma_f32 v[32:33], v[48:49], v[10:11], v[32:33] op_sel:[0,1,0] op_sel_hi:[1,1,1]
	v_cvt_pk_f32_fp8_e32 v[42:43], v66
	v_cvt_pk_f32_fp8_sdwa v[44:45], v66 src0_sel:WORD_1
	v_pk_fma_f32 v[34:35], v[42:43], v[10:11], v[34:35] op_sel:[0,1,0] op_sel_hi:[1,1,1]
	v_pk_fma_f32 v[36:37], v[44:45], v[10:11], v[36:37] op_sel:[0,1,0] op_sel_hi:[1,1,1]
	v_cvt_pk_f32_fp8_e32 v[46:47], v67
	v_cvt_pk_f32_fp8_sdwa v[48:49], v67 src0_sel:WORD_1
	v_pk_fma_f32 v[38:39], v[46:47], v[10:11], v[38:39] op_sel:[0,1,0] op_sel_hi:[1,1,1]
	v_pk_fma_f32 v[40:41], v[48:49], v[10:11], v[40:41] op_sel:[0,1,0] op_sel_hi:[1,1,1]
	v_cvt_pk_f32_fp8_e32 v[42:43], v68
	v_cvt_pk_f32_fp8_sdwa v[44:45], v68 src0_sel:WORD_1
	v_pk_fma_f32 v[26:27], v[42:43], v[12:13], v[26:27] op_sel_hi:[1,0,1]
	v_pk_fma_f32 v[28:29], v[44:45], v[12:13], v[28:29] op_sel_hi:[1,0,1]
	v_cvt_pk_f32_fp8_e32 v[46:47], v69
	v_cvt_pk_f32_fp8_sdwa v[48:49], v69 src0_sel:WORD_1
	v_pk_fma_f32 v[30:31], v[46:47], v[12:13], v[30:31] op_sel_hi:[1,0,1]
	v_pk_fma_f32 v[32:33], v[48:49], v[12:13], v[32:33] op_sel_hi:[1,0,1]
	v_cvt_pk_f32_fp8_e32 v[42:43], v70
	v_cvt_pk_f32_fp8_sdwa v[44:45], v70 src0_sel:WORD_1
	v_pk_fma_f32 v[34:35], v[42:43], v[12:13], v[34:35] op_sel_hi:[1,0,1]
	v_pk_fma_f32 v[36:37], v[44:45], v[12:13], v[36:37] op_sel_hi:[1,0,1]
	v_cvt_pk_f32_fp8_e32 v[46:47], v71
	v_cvt_pk_f32_fp8_sdwa v[48:49], v71 src0_sel:WORD_1
	v_pk_fma_f32 v[38:39], v[46:47], v[12:13], v[38:39] op_sel_hi:[1,0,1]
	v_pk_fma_f32 v[40:41], v[48:49], v[12:13], v[40:41] op_sel_hi:[1,0,1]
	v_cvt_pk_f32_fp8_e32 v[42:43], v72
	v_cvt_pk_f32_fp8_sdwa v[44:45], v72 src0_sel:WORD_1
	v_pk_fma_f32 v[26:27], v[42:43], v[12:13], v[26:27] op_sel:[0,1,0] op_sel_hi:[1,1,1]
	v_pk_fma_f32 v[28:29], v[44:45], v[12:13], v[28:29] op_sel:[0,1,0] op_sel_hi:[1,1,1]
	v_cvt_pk_f32_fp8_e32 v[46:47], v73
	v_cvt_pk_f32_fp8_sdwa v[48:49], v73 src0_sel:WORD_1
	v_pk_fma_f32 v[30:31], v[46:47], v[12:13], v[30:31] op_sel:[0,1,0] op_sel_hi:[1,1,1]
	v_pk_fma_f32 v[32:33], v[48:49], v[12:13], v[32:33] op_sel:[0,1,0] op_sel_hi:[1,1,1]
	v_cvt_pk_f32_fp8_e32 v[42:43], v74
	v_cvt_pk_f32_fp8_sdwa v[44:45], v74 src0_sel:WORD_1
	v_pk_fma_f32 v[34:35], v[42:43], v[12:13], v[34:35] op_sel:[0,1,0] op_sel_hi:[1,1,1]
	v_pk_fma_f32 v[36:37], v[44:45], v[12:13], v[36:37] op_sel:[0,1,0] op_sel_hi:[1,1,1]
	v_cvt_pk_f32_fp8_e32 v[46:47], v75
	v_cvt_pk_f32_fp8_sdwa v[48:49], v75 src0_sel:WORD_1
	v_pk_fma_f32 v[38:39], v[46:47], v[12:13], v[38:39] op_sel:[0,1,0] op_sel_hi:[1,1,1]
	v_pk_fma_f32 v[40:41], v[48:49], v[12:13], v[40:41] op_sel:[0,1,0] op_sel_hi:[1,1,1]
	v_cvt_pk_f32_fp8_e32 v[42:43], v76
	v_cvt_pk_f32_fp8_sdwa v[44:45], v76 src0_sel:WORD_1
	v_pk_fma_f32 v[26:27], v[42:43], v[14:15], v[26:27] op_sel_hi:[1,0,1]
	v_pk_fma_f32 v[28:29], v[44:45], v[14:15], v[28:29] op_sel_hi:[1,0,1]
	v_cvt_pk_f32_fp8_e32 v[46:47], v77
	v_cvt_pk_f32_fp8_sdwa v[48:49], v77 src0_sel:WORD_1
	v_pk_fma_f32 v[30:31], v[46:47], v[14:15], v[30:31] op_sel_hi:[1,0,1]
	v_pk_fma_f32 v[32:33], v[48:49], v[14:15], v[32:33] op_sel_hi:[1,0,1]
	v_cvt_pk_f32_fp8_e32 v[42:43], v78
	v_cvt_pk_f32_fp8_sdwa v[44:45], v78 src0_sel:WORD_1
	v_pk_fma_f32 v[34:35], v[42:43], v[14:15], v[34:35] op_sel_hi:[1,0,1]
	v_pk_fma_f32 v[36:37], v[44:45], v[14:15], v[36:37] op_sel_hi:[1,0,1]
	v_cvt_pk_f32_fp8_e32 v[46:47], v79
	v_cvt_pk_f32_fp8_sdwa v[48:49], v79 src0_sel:WORD_1
	v_pk_fma_f32 v[38:39], v[46:47], v[14:15], v[38:39] op_sel_hi:[1,0,1]
	v_pk_fma_f32 v[40:41], v[48:49], v[14:15], v[40:41] op_sel_hi:[1,0,1]
	v_cvt_pk_f32_fp8_e32 v[42:43], v80
	v_cvt_pk_f32_fp8_sdwa v[44:45], v80 src0_sel:WORD_1
	v_pk_fma_f32 v[26:27], v[42:43], v[14:15], v[26:27] op_sel:[0,1,0] op_sel_hi:[1,1,1]
	v_pk_fma_f32 v[28:29], v[44:45], v[14:15], v[28:29] op_sel:[0,1,0] op_sel_hi:[1,1,1]
	v_cvt_pk_f32_fp8_e32 v[46:47], v81
	v_cvt_pk_f32_fp8_sdwa v[48:49], v81 src0_sel:WORD_1
	v_pk_fma_f32 v[30:31], v[46:47], v[14:15], v[30:31] op_sel:[0,1,0] op_sel_hi:[1,1,1]
	v_pk_fma_f32 v[32:33], v[48:49], v[14:15], v[32:33] op_sel:[0,1,0] op_sel_hi:[1,1,1]
	v_cvt_pk_f32_fp8_e32 v[42:43], v82
	v_cvt_pk_f32_fp8_sdwa v[44:45], v82 src0_sel:WORD_1
	v_pk_fma_f32 v[34:35], v[42:43], v[14:15], v[34:35] op_sel:[0,1,0] op_sel_hi:[1,1,1]
	v_pk_fma_f32 v[36:37], v[44:45], v[14:15], v[36:37] op_sel:[0,1,0] op_sel_hi:[1,1,1]
	v_cvt_pk_f32_fp8_e32 v[46:47], v83
	v_cvt_pk_f32_fp8_sdwa v[48:49], v83 src0_sel:WORD_1
	v_pk_fma_f32 v[38:39], v[46:47], v[14:15], v[38:39] op_sel:[0,1,0] op_sel_hi:[1,1,1]
	v_pk_fma_f32 v[40:41], v[48:49], v[14:15], v[40:41] op_sel:[0,1,0] op_sel_hi:[1,1,1]
	v_cvt_pk_f32_fp8_e32 v[42:43], v84
	v_cvt_pk_f32_fp8_sdwa v[44:45], v84 src0_sel:WORD_1
	v_pk_fma_f32 v[26:27], v[42:43], v[16:17], v[26:27] op_sel_hi:[1,0,1]
	v_pk_fma_f32 v[28:29], v[44:45], v[16:17], v[28:29] op_sel_hi:[1,0,1]
	v_cvt_pk_f32_fp8_e32 v[46:47], v85
	v_cvt_pk_f32_fp8_sdwa v[48:49], v85 src0_sel:WORD_1
	v_pk_fma_f32 v[30:31], v[46:47], v[16:17], v[30:31] op_sel_hi:[1,0,1]
	v_pk_fma_f32 v[32:33], v[48:49], v[16:17], v[32:33] op_sel_hi:[1,0,1]
	v_cvt_pk_f32_fp8_e32 v[42:43], v86
	v_cvt_pk_f32_fp8_sdwa v[44:45], v86 src0_sel:WORD_1
	v_pk_fma_f32 v[34:35], v[42:43], v[16:17], v[34:35] op_sel_hi:[1,0,1]
	v_pk_fma_f32 v[36:37], v[44:45], v[16:17], v[36:37] op_sel_hi:[1,0,1]
	v_cvt_pk_f32_fp8_e32 v[46:47], v87
	v_cvt_pk_f32_fp8_sdwa v[48:49], v87 src0_sel:WORD_1
	v_pk_fma_f32 v[38:39], v[46:47], v[16:17], v[38:39] op_sel_hi:[1,0,1]
	v_pk_fma_f32 v[40:41], v[48:49], v[16:17], v[40:41] op_sel_hi:[1,0,1]
	v_cvt_pk_f32_fp8_e32 v[42:43], v88
	v_cvt_pk_f32_fp8_sdwa v[44:45], v88 src0_sel:WORD_1
	v_pk_fma_f32 v[26:27], v[42:43], v[16:17], v[26:27] op_sel:[0,1,0] op_sel_hi:[1,1,1]
	v_pk_fma_f32 v[28:29], v[44:45], v[16:17], v[28:29] op_sel:[0,1,0] op_sel_hi:[1,1,1]
	v_cvt_pk_f32_fp8_e32 v[46:47], v89
	v_cvt_pk_f32_fp8_sdwa v[48:49], v89 src0_sel:WORD_1
	v_pk_fma_f32 v[30:31], v[46:47], v[16:17], v[30:31] op_sel:[0,1,0] op_sel_hi:[1,1,1]
	v_pk_fma_f32 v[32:33], v[48:49], v[16:17], v[32:33] op_sel:[0,1,0] op_sel_hi:[1,1,1]
	v_cvt_pk_f32_fp8_e32 v[42:43], v90
	v_cvt_pk_f32_fp8_sdwa v[44:45], v90 src0_sel:WORD_1
	v_pk_fma_f32 v[34:35], v[42:43], v[16:17], v[34:35] op_sel:[0,1,0] op_sel_hi:[1,1,1]
	v_pk_fma_f32 v[36:37], v[44:45], v[16:17], v[36:37] op_sel:[0,1,0] op_sel_hi:[1,1,1]
	v_cvt_pk_f32_fp8_e32 v[46:47], v91
	v_cvt_pk_f32_fp8_sdwa v[48:49], v91 src0_sel:WORD_1
	v_pk_fma_f32 v[38:39], v[46:47], v[16:17], v[38:39] op_sel:[0,1,0] op_sel_hi:[1,1,1]
	v_pk_fma_f32 v[40:41], v[48:49], v[16:17], v[40:41] op_sel:[0,1,0] op_sel_hi:[1,1,1]
	v_cvt_pk_f32_fp8_e32 v[42:43], v92
	v_cvt_pk_f32_fp8_sdwa v[44:45], v92 src0_sel:WORD_1
	v_pk_fma_f32 v[26:27], v[42:43], v[18:19], v[26:27] op_sel_hi:[1,0,1]
	v_pk_fma_f32 v[28:29], v[44:45], v[18:19], v[28:29] op_sel_hi:[1,0,1]
	v_cvt_pk_f32_fp8_e32 v[46:47], v93
	v_cvt_pk_f32_fp8_sdwa v[48:49], v93 src0_sel:WORD_1
	v_pk_fma_f32 v[30:31], v[46:47], v[18:19], v[30:31] op_sel_hi:[1,0,1]
	v_pk_fma_f32 v[32:33], v[48:49], v[18:19], v[32:33] op_sel_hi:[1,0,1]
	v_cvt_pk_f32_fp8_e32 v[42:43], v94
	v_cvt_pk_f32_fp8_sdwa v[44:45], v94 src0_sel:WORD_1
	v_pk_fma_f32 v[34:35], v[42:43], v[18:19], v[34:35] op_sel_hi:[1,0,1]
	v_pk_fma_f32 v[36:37], v[44:45], v[18:19], v[36:37] op_sel_hi:[1,0,1]
	v_cvt_pk_f32_fp8_e32 v[46:47], v95
	v_cvt_pk_f32_fp8_sdwa v[48:49], v95 src0_sel:WORD_1
	v_pk_fma_f32 v[38:39], v[46:47], v[18:19], v[38:39] op_sel_hi:[1,0,1]
	v_pk_fma_f32 v[40:41], v[48:49], v[18:19], v[40:41] op_sel_hi:[1,0,1]
	v_cvt_pk_f32_fp8_e32 v[42:43], v96
	v_cvt_pk_f32_fp8_sdwa v[44:45], v96 src0_sel:WORD_1
	v_pk_fma_f32 v[26:27], v[42:43], v[18:19], v[26:27] op_sel:[0,1,0] op_sel_hi:[1,1,1]
	v_pk_fma_f32 v[28:29], v[44:45], v[18:19], v[28:29] op_sel:[0,1,0] op_sel_hi:[1,1,1]
	v_cvt_pk_f32_fp8_e32 v[46:47], v97
	v_cvt_pk_f32_fp8_sdwa v[48:49], v97 src0_sel:WORD_1
	v_pk_fma_f32 v[30:31], v[46:47], v[18:19], v[30:31] op_sel:[0,1,0] op_sel_hi:[1,1,1]
	v_pk_fma_f32 v[32:33], v[48:49], v[18:19], v[32:33] op_sel:[0,1,0] op_sel_hi:[1,1,1]
	v_cvt_pk_f32_fp8_e32 v[42:43], v98
	v_cvt_pk_f32_fp8_sdwa v[44:45], v98 src0_sel:WORD_1
	v_pk_fma_f32 v[34:35], v[42:43], v[18:19], v[34:35] op_sel:[0,1,0] op_sel_hi:[1,1,1]
	v_pk_fma_f32 v[36:37], v[44:45], v[18:19], v[36:37] op_sel:[0,1,0] op_sel_hi:[1,1,1]
	v_cvt_pk_f32_fp8_e32 v[46:47], v99
	v_cvt_pk_f32_fp8_sdwa v[48:49], v99 src0_sel:WORD_1
	v_pk_fma_f32 v[38:39], v[46:47], v[18:19], v[38:39] op_sel:[0,1,0] op_sel_hi:[1,1,1]
	v_pk_fma_f32 v[40:41], v[48:49], v[18:19], v[40:41] op_sel:[0,1,0] op_sel_hi:[1,1,1]
	v_cvt_pk_f32_fp8_e32 v[42:43], v100
	v_cvt_pk_f32_fp8_sdwa v[44:45], v100 src0_sel:WORD_1
	v_pk_fma_f32 v[26:27], v[42:43], v[20:21], v[26:27] op_sel_hi:[1,0,1]
	v_pk_fma_f32 v[28:29], v[44:45], v[20:21], v[28:29] op_sel_hi:[1,0,1]
	v_cvt_pk_f32_fp8_e32 v[46:47], v101
	v_cvt_pk_f32_fp8_sdwa v[48:49], v101 src0_sel:WORD_1
	v_pk_fma_f32 v[30:31], v[46:47], v[20:21], v[30:31] op_sel_hi:[1,0,1]
	v_pk_fma_f32 v[32:33], v[48:49], v[20:21], v[32:33] op_sel_hi:[1,0,1]
	v_cvt_pk_f32_fp8_e32 v[42:43], v102
	v_cvt_pk_f32_fp8_sdwa v[44:45], v102 src0_sel:WORD_1
	v_pk_fma_f32 v[34:35], v[42:43], v[20:21], v[34:35] op_sel_hi:[1,0,1]
	v_pk_fma_f32 v[36:37], v[44:45], v[20:21], v[36:37] op_sel_hi:[1,0,1]
	v_cvt_pk_f32_fp8_e32 v[46:47], v103
	v_cvt_pk_f32_fp8_sdwa v[48:49], v103 src0_sel:WORD_1
	v_pk_fma_f32 v[38:39], v[46:47], v[20:21], v[38:39] op_sel_hi:[1,0,1]
	v_pk_fma_f32 v[40:41], v[48:49], v[20:21], v[40:41] op_sel_hi:[1,0,1]
	v_cvt_pk_f32_fp8_e32 v[42:43], v104
	v_cvt_pk_f32_fp8_sdwa v[44:45], v104 src0_sel:WORD_1
	v_pk_fma_f32 v[26:27], v[42:43], v[20:21], v[26:27] op_sel:[0,1,0] op_sel_hi:[1,1,1]
	v_pk_fma_f32 v[28:29], v[44:45], v[20:21], v[28:29] op_sel:[0,1,0] op_sel_hi:[1,1,1]
	v_cvt_pk_f32_fp8_e32 v[46:47], v105
	v_cvt_pk_f32_fp8_sdwa v[48:49], v105 src0_sel:WORD_1
	v_pk_fma_f32 v[30:31], v[46:47], v[20:21], v[30:31] op_sel:[0,1,0] op_sel_hi:[1,1,1]
	v_pk_fma_f32 v[32:33], v[48:49], v[20:21], v[32:33] op_sel:[0,1,0] op_sel_hi:[1,1,1]
	v_cvt_pk_f32_fp8_e32 v[42:43], v106
	v_cvt_pk_f32_fp8_sdwa v[44:45], v106 src0_sel:WORD_1
; __device__ __forceinline__ float wsum(float v) { v = dpp_row_sum16(v); v += __shfl_xor(v, 16); v += __shfl_xor(v, 32); return v; }
; __device__ __forceinline__ void phase5(const Params& p, char* smem, const bool store_x = true) {
;     ...
;     float x2[16];
; #pragma unroll
;     for (int i = 0; i < 4; i++) {
;       const float4 xv = i == 0 ? xv0 : i == 1 ? xv1 : i == 2 ? xv2 : xv3;
;       x2[4 * i] = xv.x + o2[2 * i].x; x2[4 * i + 1] = xv.y + o2[2 * i].y; x2[4 * i + 2] = xv.z + o2[2 * i + 1].x; x2[4 * i + 3] = xv.w + o2[2 * i + 1].y;
;     }
;     float ss = 0.f;
; #pragma unroll
;     for (int i = 0; i < 16; i++) ss += x2[i] * x2[i];
;     ss = wsum(ss);
;     const float rs = rsqrtf(ss * (1.f / 1024.f) + EPSF);
;     if (store_x) {
; #pragma unroll
;       for (int i = 0; i < 4; i++) *(float4*)(xr + i * 4) = make_float4(x2[4 * i], x2[4 * i + 1], x2[4 * i + 2], x2[4 * i + 3]);
;     }
	v_pk_fma_f32 v[34:35], v[42:43], v[20:21], v[34:35] op_sel:[0,1,0] op_sel_hi:[1,1,1]
	v_pk_fma_f32 v[36:37], v[44:45], v[20:21], v[36:37] op_sel:[0,1,0] op_sel_hi:[1,1,1]
	v_cvt_pk_f32_fp8_e32 v[46:47], v107
	v_cvt_pk_f32_fp8_sdwa v[48:49], v107 src0_sel:WORD_1
	v_pk_fma_f32 v[38:39], v[46:47], v[20:21], v[38:39] op_sel:[0,1,0] op_sel_hi:[1,1,1]
	v_pk_fma_f32 v[40:41], v[48:49], v[20:21], v[40:41] op_sel:[0,1,0] op_sel_hi:[1,1,1]
	v_cvt_pk_f32_fp8_e32 v[42:43], v108
	v_cvt_pk_f32_fp8_sdwa v[44:45], v108 src0_sel:WORD_1
	v_pk_fma_f32 v[26:27], v[42:43], v[22:23], v[26:27] op_sel_hi:[1,0,1]
	v_pk_fma_f32 v[28:29], v[44:45], v[22:23], v[28:29] op_sel_hi:[1,0,1]
	v_cvt_pk_f32_fp8_e32 v[46:47], v109
	v_cvt_pk_f32_fp8_sdwa v[48:49], v109 src0_sel:WORD_1
	v_pk_fma_f32 v[30:31], v[46:47], v[22:23], v[30:31] op_sel_hi:[1,0,1]
	v_pk_fma_f32 v[32:33], v[48:49], v[22:23], v[32:33] op_sel_hi:[1,0,1]
	v_cvt_pk_f32_fp8_e32 v[42:43], v110
	v_cvt_pk_f32_fp8_sdwa v[44:45], v110 src0_sel:WORD_1
	v_pk_fma_f32 v[34:35], v[42:43], v[22:23], v[34:35] op_sel_hi:[1,0,1]
	v_pk_fma_f32 v[36:37], v[44:45], v[22:23], v[36:37] op_sel_hi:[1,0,1]
	v_cvt_pk_f32_fp8_e32 v[46:47], v111
	v_cvt_pk_f32_fp8_sdwa v[48:49], v111 src0_sel:WORD_1
	v_pk_fma_f32 v[38:39], v[46:47], v[22:23], v[38:39] op_sel_hi:[1,0,1]
	v_pk_fma_f32 v[40:41], v[48:49], v[22:23], v[40:41] op_sel_hi:[1,0,1]
	v_cvt_pk_f32_fp8_e32 v[42:43], v112
	v_cvt_pk_f32_fp8_sdwa v[44:45], v112 src0_sel:WORD_1
	v_pk_fma_f32 v[26:27], v[42:43], v[22:23], v[26:27] op_sel:[0,1,0] op_sel_hi:[1,1,1]
	v_pk_fma_f32 v[28:29], v[44:45], v[22:23], v[28:29] op_sel:[0,1,0] op_sel_hi:[1,1,1]
	v_cvt_pk_f32_fp8_e32 v[46:47], v113
	v_cvt_pk_f32_fp8_sdwa v[48:49], v113 src0_sel:WORD_1
	v_pk_fma_f32 v[30:31], v[46:47], v[22:23], v[30:31] op_sel:[0,1,0] op_sel_hi:[1,1,1]
	v_pk_fma_f32 v[32:33], v[48:49], v[22:23], v[32:33] op_sel:[0,1,0] op_sel_hi:[1,1,1]
	v_cvt_pk_f32_fp8_e32 v[42:43], v114
	v_cvt_pk_f32_fp8_sdwa v[44:45], v114 src0_sel:WORD_1
	v_pk_fma_f32 v[34:35], v[42:43], v[22:23], v[34:35] op_sel:[0,1,0] op_sel_hi:[1,1,1]
	v_pk_fma_f32 v[36:37], v[44:45], v[22:23], v[36:37] op_sel:[0,1,0] op_sel_hi:[1,1,1]
	v_cvt_pk_f32_fp8_e32 v[46:47], v115
	v_cvt_pk_f32_fp8_sdwa v[48:49], v115 src0_sel:WORD_1
	v_pk_fma_f32 v[38:39], v[46:47], v[22:23], v[38:39] op_sel:[0,1,0] op_sel_hi:[1,1,1]
	v_pk_fma_f32 v[40:41], v[48:49], v[22:23], v[40:41] op_sel:[0,1,0] op_sel_hi:[1,1,1]
	v_cvt_pk_f32_fp8_e32 v[42:43], v116
	v_cvt_pk_f32_fp8_sdwa v[44:45], v116 src0_sel:WORD_1
	v_pk_fma_f32 v[26:27], v[42:43], v[24:25], v[26:27] op_sel_hi:[1,0,1]
	v_pk_fma_f32 v[28:29], v[44:45], v[24:25], v[28:29] op_sel_hi:[1,0,1]
	v_cvt_pk_f32_fp8_e32 v[46:47], v117
	v_cvt_pk_f32_fp8_sdwa v[48:49], v117 src0_sel:WORD_1
	v_pk_fma_f32 v[30:31], v[46:47], v[24:25], v[30:31] op_sel_hi:[1,0,1]
	v_pk_fma_f32 v[32:33], v[48:49], v[24:25], v[32:33] op_sel_hi:[1,0,1]
	v_cvt_pk_f32_fp8_e32 v[42:43], v118
	v_cvt_pk_f32_fp8_sdwa v[44:45], v118 src0_sel:WORD_1
	v_pk_fma_f32 v[34:35], v[42:43], v[24:25], v[34:35] op_sel_hi:[1,0,1]
	v_pk_fma_f32 v[36:37], v[44:45], v[24:25], v[36:37] op_sel_hi:[1,0,1]
	v_cvt_pk_f32_fp8_e32 v[46:47], v119
	v_cvt_pk_f32_fp8_sdwa v[48:49], v119 src0_sel:WORD_1
	v_pk_fma_f32 v[38:39], v[46:47], v[24:25], v[38:39] op_sel_hi:[1,0,1]
	v_pk_fma_f32 v[40:41], v[48:49], v[24:25], v[40:41] op_sel_hi:[1,0,1]
	v_cvt_pk_f32_fp8_e32 v[42:43], v120
	v_cvt_pk_f32_fp8_sdwa v[44:45], v120 src0_sel:WORD_1
	v_pk_fma_f32 v[26:27], v[42:43], v[24:25], v[26:27] op_sel:[0,1,0] op_sel_hi:[1,1,1]
	v_pk_fma_f32 v[28:29], v[44:45], v[24:25], v[28:29] op_sel:[0,1,0] op_sel_hi:[1,1,1]
	v_cvt_pk_f32_fp8_e32 v[46:47], v121
	v_cvt_pk_f32_fp8_sdwa v[48:49], v121 src0_sel:WORD_1
	v_pk_fma_f32 v[30:31], v[46:47], v[24:25], v[30:31] op_sel:[0,1,0] op_sel_hi:[1,1,1]
	v_pk_fma_f32 v[32:33], v[48:49], v[24:25], v[32:33] op_sel:[0,1,0] op_sel_hi:[1,1,1]
	v_cvt_pk_f32_fp8_e32 v[42:43], v122
	v_cvt_pk_f32_fp8_sdwa v[44:45], v122 src0_sel:WORD_1
	v_pk_fma_f32 v[34:35], v[42:43], v[24:25], v[34:35] op_sel:[0,1,0] op_sel_hi:[1,1,1]
	v_pk_fma_f32 v[36:37], v[44:45], v[24:25], v[36:37] op_sel:[0,1,0] op_sel_hi:[1,1,1]
	v_cvt_pk_f32_fp8_e32 v[46:47], v123
	v_cvt_pk_f32_fp8_sdwa v[48:49], v123 src0_sel:WORD_1
	v_pk_fma_f32 v[38:39], v[46:47], v[24:25], v[38:39] op_sel:[0,1,0] op_sel_hi:[1,1,1]
	v_pk_fma_f32 v[40:41], v[48:49], v[24:25], v[40:41] op_sel:[0,1,0] op_sel_hi:[1,1,1]
	s_nop 1
	v_permlane32_swap_b32_e32 v26, v34
	v_permlane32_swap_b32_e32 v27, v35
	v_permlane32_swap_b32_e32 v28, v36
	v_permlane32_swap_b32_e32 v29, v37
	v_permlane32_swap_b32_e32 v30, v38
	v_permlane32_swap_b32_e32 v31, v39
	v_permlane32_swap_b32_e32 v32, v40
	v_permlane32_swap_b32_e32 v33, v41
	v_add_f32_e32 v26, v26, v34
	v_add_f32_e32 v27, v27, v35
	v_add_f32_e32 v28, v28, v36
	v_add_f32_e32 v29, v29, v37
	v_add_f32_e32 v30, v30, v38
	v_add_f32_e32 v31, v31, v39
	v_add_f32_e32 v32, v32, v40
	v_add_f32_e32 v33, v33, v41
	s_nop 1
	v_permlane16_swap_b32_e32 v26, v30
	v_permlane16_swap_b32_e32 v27, v31
	v_permlane16_swap_b32_e32 v28, v32
	v_permlane16_swap_b32_e32 v29, v33
	v_add_f32_e32 v26, v26, v30
	v_add_f32_e32 v27, v27, v31
	v_add_f32_e32 v28, v28, v32
	v_add_f32_e32 v29, v29, v33
	s_lshl_b32 s11, s12, 12
	v_add_u32_e32 v6, s11, v3
	v_add_f32_dpp v42, v26, v26 row_ror:8 row_mask:0xf bank_mask:0xf
	v_add_f32_dpp v43, v28, v28 row_ror:8 row_mask:0xf bank_mask:0xf
	v_add_f32_dpp v44, v27, v27 row_ror:8 row_mask:0xf bank_mask:0xf
	v_add_f32_dpp v45, v29, v29 row_ror:8 row_mask:0xf bank_mask:0xf
	v_cndmask_b32_e64 v46, v42, v43, s[14:15]
	v_cndmask_b32_e64 v47, v44, v45, s[14:15]
	v_add_f32_e32 v46, v50, v46
	v_add_f32_e32 v47, v51, v47
	global_store_dwordx2 v6, v[46:47], s[6:7]
	v_mul_f32_e32 v48, v46, v46
	v_fmac_f32_e32 v48, v47, v47
	s_lshl_b32 s11, s12, 2
	s_add_u32 s11, s11, 0x1100000
	v_mov_b32_e32 v7, s11
	v_add_f32_dpp v48, v48, v48 quad_perm:[1,0,3,2] row_mask:0xf bank_mask:0xf
	s_nop 1
	v_add_f32_dpp v48, v48, v48 quad_perm:[2,3,0,1] row_mask:0xf bank_mask:0xf
	s_nop 1
	v_add_f32_dpp v48, v48, v48 row_half_mirror row_mask:0xf bank_mask:0xf
	s_nop 1
	v_add_f32_dpp v48, v48, v48 row_mirror row_mask:0xf bank_mask:0xf
	s_nop 1
	v_add_f32_dpp v48, v48, v48 row_bcast:15 row_mask:0xa bank_mask:0xf
	s_nop 1
	v_add_f32_dpp v48, v48, v48 row_bcast:31 row_mask:0xc bank_mask:0xf
	s_nop 1
	s_mov_b32 exec_lo, 0
	s_brev_b32 exec_hi, 1
	global_atomic_add_f32 v7, v48, s[4:5]
	s_mov_b64 exec, -1
; #define P5_LOAD(A, TAB, j0)                                                                \
;   _Pragma("unroll") for (int q = 0; q < 16; q++) {                                         \
;     A[q] = ((const uint4*)((TAB) + (size_t)widx[(j0) + q] * 1024))[lane];                  \
;   }
; __device__ __forceinline__ void phase5(const Params& p, char* smem, const bool store_x = true) {
;     ...
; #pragma unroll 1
;     for (int j0 = 0; j0 < 128; j0 += 32) {
;       P5_LOAD(A1, EV, j0 + 16)
;       P5_COMPUTE_V(A0, j0)
;       if (j0 + 32 < 128) { P5_LOAD(A0, EV, j0 + 32) }
;       P5_COMPUTE_V(A1, j0 + 16)
;     }
.Lp5v_skip0:
	s_add_u32 s10, s8, s28
	s_min_u32 s10, s10, s13
	s_lshl_b32 s18, s10, 10
	s_add_u32 s11, s16, 9
	s_and_b32 s11, s11, 15
	s_lshl_b32 s11, s11, 10
	s_add_u32 s11, s11, s17
	s_mov_b32 m0, s11
	v_lshl_add_u64 v[4:5], v[58:59], 0, s[18:19]
	global_load_lds_dwordx4 v[4:5], off
	s_add_u32 s11, s16, 4
	s_and_b32 s11, s11, 15
	s_lshl_b32 s11, s11, 10
	v_add_u32_e32 v8, s11, v2
	ds_read_b128 v[10:13], v8 offset:0
	ds_read_b128 v[14:17], v8 offset:16
	ds_read_b128 v[18:21], v8 offset:32
	ds_read_b128 v[22:25], v8 offset:48
	s_add_u32 s10, s8, s23
	s_min_u32 s10, s10, s13
	s_lshl_b32 s11, s10, 12
	v_add_u32_e32 v6, s11, v3
	global_load_dwordx2 v[50:51], v6, s[6:7]
	s_waitcnt lgkmcnt(0)
	v_add_u32_e32 v10, v10, v1
	global_load_dwordx4 v[60:63], v10, s[2:3]
	v_add_u32_e32 v11, v11, v1
	global_load_dwordx4 v[64:67], v11, s[2:3]
	v_add_u32_e32 v12, v12, v1
	global_load_dwordx4 v[68:71], v12, s[2:3]
	v_add_u32_e32 v13, v13, v1
	global_load_dwordx4 v[72:75], v13, s[2:3]
	v_add_u32_e32 v14, v14, v1
	global_load_dwordx4 v[76:79], v14, s[2:3]
	v_add_u32_e32 v15, v15, v1
	global_load_dwordx4 v[80:83], v15, s[2:3]
	v_add_u32_e32 v16, v16, v1
	global_load_dwordx4 v[84:87], v16, s[2:3]
	v_add_u32_e32 v17, v17, v1
	global_load_dwordx4 v[88:91], v17, s[2:3]
	v_add_u32_e32 v18, v18, v1
	global_load_dwordx4 v[92:95], v18, s[2:3]
	v_add_u32_e32 v19, v19, v1
	global_load_dwordx4 v[96:99], v19, s[2:3]
	v_add_u32_e32 v20, v20, v1
	global_load_dwordx4 v[100:103], v20, s[2:3]
	v_add_u32_e32 v21, v21, v1
	global_load_dwordx4 v[104:107], v21, s[2:3]
	v_add_u32_e32 v22, v22, v1
	global_load_dwordx4 v[108:111], v22, s[2:3]
	v_add_u32_e32 v23, v23, v1
	global_load_dwordx4 v[112:115], v23, s[2:3]
	v_add_u32_e32 v24, v24, v1
	global_load_dwordx4 v[116:119], v24, s[2:3]
	v_add_u32_e32 v25, v25, v1
	global_load_dwordx4 v[120:123], v25, s[2:3]
	s_add_u32 s11, s16, 1
	s_and_b32 s11, s11, 15
	s_lshl_b32 s11, s11, 10
	v_add_u32_e32 v8, s11, v2
	ds_read_b128 v[10:13], v8 offset:512
	ds_read_b128 v[14:17], v8 offset:528
	ds_read_b128 v[18:21], v8 offset:544
	ds_read_b128 v[22:25], v8 offset:560
	s_add_u32 s12, s8, s20
	s_waitcnt vmcnt(60) lgkmcnt(0)
	s_cmp_lt_u32 s12, 0x4200
	s_cbranch_scc0 .Lp5v_skip1
	v_cvt_pk_f32_fp8_e32 v[42:43], v124
	v_cvt_pk_f32_fp8_sdwa v[44:45], v124 src0_sel:WORD_1
	v_pk_mul_f32 v[26:27], v[42:43], v[10:11] op_sel_hi:[1,0]
	v_pk_mul_f32 v[28:29], v[44:45], v[10:11] op_sel_hi:[1,0]
	v_cvt_pk_f32_fp8_e32 v[46:47], v125
	v_cvt_pk_f32_fp8_sdwa v[48:49], v125 src0_sel:WORD_1
	v_pk_mul_f32 v[30:31], v[46:47], v[10:11] op_sel_hi:[1,0]
	v_pk_mul_f32 v[32:33], v[48:49], v[10:11] op_sel_hi:[1,0]
	v_cvt_pk_f32_fp8_e32 v[42:43], v126
	v_cvt_pk_f32_fp8_sdwa v[44:45], v126 src0_sel:WORD_1
	v_pk_mul_f32 v[34:35], v[42:43], v[10:11] op_sel_hi:[1,0]
	v_pk_mul_f32 v[36:37], v[44:45], v[10:11] op_sel_hi:[1,0]
	v_cvt_pk_f32_fp8_e32 v[46:47], v127
	v_cvt_pk_f32_fp8_sdwa v[48:49], v127 src0_sel:WORD_1
	v_pk_mul_f32 v[38:39], v[46:47], v[10:11] op_sel_hi:[1,0]
	v_pk_mul_f32 v[40:41], v[48:49], v[10:11] op_sel_hi:[1,0]
	v_cvt_pk_f32_fp8_e32 v[42:43], v128
	v_cvt_pk_f32_fp8_sdwa v[44:45], v128 src0_sel:WORD_1
	v_pk_fma_f32 v[26:27], v[42:43], v[10:11], v[26:27] op_sel:[0,1,0] op_sel_hi:[1,1,1]
	v_pk_fma_f32 v[28:29], v[44:45], v[10:11], v[28:29] op_sel:[0,1,0] op_sel_hi:[1,1,1]
	v_cvt_pk_f32_fp8_e32 v[46:47], v129
	v_cvt_pk_f32_fp8_sdwa v[48:49], v129 src0_sel:WORD_1
	v_pk_fma_f32 v[30:31], v[46:47], v[10:11], v[30:31] op_sel:[0,1,0] op_sel_hi:[1,1,1]
	v_pk_fma_f32 v[32:33], v[48:49], v[10:11], v[32:33] op_sel:[0,1,0] op_sel_hi:[1,1,1]
	v_cvt_pk_f32_fp8_e32 v[42:43], v130
	v_cvt_pk_f32_fp8_sdwa v[44:45], v130 src0_sel:WORD_1
	v_pk_fma_f32 v[34:35], v[42:43], v[10:11], v[34:35] op_sel:[0,1,0] op_sel_hi:[1,1,1]
	v_pk_fma_f32 v[36:37], v[44:45], v[10:11], v[36:37] op_sel:[0,1,0] op_sel_hi:[1,1,1]
	v_cvt_pk_f32_fp8_e32 v[46:47], v131
	v_cvt_pk_f32_fp8_sdwa v[48:49], v131 src0_sel:WORD_1
	v_pk_fma_f32 v[38:39], v[46:47], v[10:11], v[38:39] op_sel:[0,1,0] op_sel_hi:[1,1,1]
	v_pk_fma_f32 v[40:41], v[48:49], v[10:11], v[40:41] op_sel:[0,1,0] op_sel_hi:[1,1,1]
	v_cvt_pk_f32_fp8_e32 v[42:43], v132
	v_cvt_pk_f32_fp8_sdwa v[44:45], v132 src0_sel:WORD_1
	v_pk_fma_f32 v[26:27], v[42:43], v[12:13], v[26:27] op_sel_hi:[1,0,1]
	v_pk_fma_f32 v[28:29], v[44:45], v[12:13], v[28:29] op_sel_hi:[1,0,1]
	v_cvt_pk_f32_fp8_e32 v[46:47], v133
	v_cvt_pk_f32_fp8_sdwa v[48:49], v133 src0_sel:WORD_1
	v_pk_fma_f32 v[30:31], v[46:47], v[12:13], v[30:31] op_sel_hi:[1,0,1]
	v_pk_fma_f32 v[32:33], v[48:49], v[12:13], v[32:33] op_sel_hi:[1,0,1]
	v_cvt_pk_f32_fp8_e32 v[42:43], v134
	v_cvt_pk_f32_fp8_sdwa v[44:45], v134 src0_sel:WORD_1
	v_pk_fma_f32 v[34:35], v[42:43], v[12:13], v[34:35] op_sel_hi:[1,0,1]
	v_pk_fma_f32 v[36:37], v[44:45], v[12:13], v[36:37] op_sel_hi:[1,0,1]
	v_cvt_pk_f32_fp8_e32 v[46:47], v135
	v_cvt_pk_f32_fp8_sdwa v[48:49], v135 src0_sel:WORD_1
	v_pk_fma_f32 v[38:39], v[46:47], v[12:13], v[38:39] op_sel_hi:[1,0,1]
	v_pk_fma_f32 v[40:41], v[48:49], v[12:13], v[40:41] op_sel_hi:[1,0,1]
	v_cvt_pk_f32_fp8_e32 v[42:43], v136
	v_cvt_pk_f32_fp8_sdwa v[44:45], v136 src0_sel:WORD_1
	v_pk_fma_f32 v[26:27], v[42:43], v[12:13], v[26:27] op_sel:[0,1,0] op_sel_hi:[1,1,1]
	v_pk_fma_f32 v[28:29], v[44:45], v[12:13], v[28:29] op_sel:[0,1,0] op_sel_hi:[1,1,1]
	v_cvt_pk_f32_fp8_e32 v[46:47], v137
	v_cvt_pk_f32_fp8_sdwa v[48:49], v137 src0_sel:WORD_1
	v_pk_fma_f32 v[30:31], v[46:47], v[12:13], v[30:31] op_sel:[0,1,0] op_sel_hi:[1,1,1]
	v_pk_fma_f32 v[32:33], v[48:49], v[12:13], v[32:33] op_sel:[0,1,0] op_sel_hi:[1,1,1]
	v_cvt_pk_f32_fp8_e32 v[42:43], v138
	v_cvt_pk_f32_fp8_sdwa v[44:45], v138 src0_sel:WORD_1
	v_pk_fma_f32 v[34:35], v[42:43], v[12:13], v[34:35] op_sel:[0,1,0] op_sel_hi:[1,1,1]
	v_pk_fma_f32 v[36:37], v[44:45], v[12:13], v[36:37] op_sel:[0,1,0] op_sel_hi:[1,1,1]
	v_cvt_pk_f32_fp8_e32 v[46:47], v139
	v_cvt_pk_f32_fp8_sdwa v[48:49], v139 src0_sel:WORD_1
	v_pk_fma_f32 v[38:39], v[46:47], v[12:13], v[38:39] op_sel:[0,1,0] op_sel_hi:[1,1,1]
	v_pk_fma_f32 v[40:41], v[48:49], v[12:13], v[40:41] op_sel:[0,1,0] op_sel_hi:[1,1,1]
	v_cvt_pk_f32_fp8_e32 v[42:43], v140
	v_cvt_pk_f32_fp8_sdwa v[44:45], v140 src0_sel:WORD_1
	v_pk_fma_f32 v[26:27], v[42:43], v[14:15], v[26:27] op_sel_hi:[1,0,1]
	v_pk_fma_f32 v[28:29], v[44:45], v[14:15], v[28:29] op_sel_hi:[1,0,1]
	v_cvt_pk_f32_fp8_e32 v[46:47], v141
	v_cvt_pk_f32_fp8_sdwa v[48:49], v141 src0_sel:WORD_1
	v_pk_fma_f32 v[30:31], v[46:47], v[14:15], v[30:31] op_sel_hi:[1,0,1]
	v_pk_fma_f32 v[32:33], v[48:49], v[14:15], v[32:33] op_sel_hi:[1,0,1]
	v_cvt_pk_f32_fp8_e32 v[42:43], v142
	v_cvt_pk_f32_fp8_sdwa v[44:45], v142 src0_sel:WORD_1
	v_pk_fma_f32 v[34:35], v[42:43], v[14:15], v[34:35] op_sel_hi:[1,0,1]
	v_pk_fma_f32 v[36:37], v[44:45], v[14:15], v[36:37] op_sel_hi:[1,0,1]
	v_cvt_pk_f32_fp8_e32 v[46:47], v143
	v_cvt_pk_f32_fp8_sdwa v[48:49], v143 src0_sel:WORD_1
	v_pk_fma_f32 v[38:39], v[46:47], v[14:15], v[38:39] op_sel_hi:[1,0,1]
	v_pk_fma_f32 v[40:41], v[48:49], v[14:15], v[40:41] op_sel_hi:[1,0,1]
	v_cvt_pk_f32_fp8_e32 v[42:43], v144
	v_cvt_pk_f32_fp8_sdwa v[44:45], v144 src0_sel:WORD_1
	v_pk_fma_f32 v[26:27], v[42:43], v[14:15], v[26:27] op_sel:[0,1,0] op_sel_hi:[1,1,1]
	v_pk_fma_f32 v[28:29], v[44:45], v[14:15], v[28:29] op_sel:[0,1,0] op_sel_hi:[1,1,1]
	v_cvt_pk_f32_fp8_e32 v[46:47], v145
	v_cvt_pk_f32_fp8_sdwa v[48:49], v145 src0_sel:WORD_1
	v_pk_fma_f32 v[30:31], v[46:47], v[14:15], v[30:31] op_sel:[0,1,0] op_sel_hi:[1,1,1]
	v_pk_fma_f32 v[32:33], v[48:49], v[14:15], v[32:33] op_sel:[0,1,0] op_sel_hi:[1,1,1]
	v_cvt_pk_f32_fp8_e32 v[42:43], v146
	v_cvt_pk_f32_fp8_sdwa v[44:45], v146 src0_sel:WORD_1
	v_pk_fma_f32 v[34:35], v[42:43], v[14:15], v[34:35] op_sel:[0,1,0] op_sel_hi:[1,1,1]
	v_pk_fma_f32 v[36:37], v[44:45], v[14:15], v[36:37] op_sel:[0,1,0] op_sel_hi:[1,1,1]
	v_cvt_pk_f32_fp8_e32 v[46:47], v147
	v_cvt_pk_f32_fp8_sdwa v[48:49], v147 src0_sel:WORD_1
	v_pk_fma_f32 v[38:39], v[46:47], v[14:15], v[38:39] op_sel:[0,1,0] op_sel_hi:[1,1,1]
	v_pk_fma_f32 v[40:41], v[48:49], v[14:15], v[40:41] op_sel:[0,1,0] op_sel_hi:[1,1,1]
	v_cvt_pk_f32_fp8_e32 v[42:43], v148
	v_cvt_pk_f32_fp8_sdwa v[44:45], v148 src0_sel:WORD_1
	v_pk_fma_f32 v[26:27], v[42:43], v[16:17], v[26:27] op_sel_hi:[1,0,1]
	v_pk_fma_f32 v[28:29], v[44:45], v[16:17], v[28:29] op_sel_hi:[1,0,1]
	v_cvt_pk_f32_fp8_e32 v[46:47], v149
	v_cvt_pk_f32_fp8_sdwa v[48:49], v149 src0_sel:WORD_1
	v_pk_fma_f32 v[30:31], v[46:47], v[16:17], v[30:31] op_sel_hi:[1,0,1]
	v_pk_fma_f32 v[32:33], v[48:49], v[16:17], v[32:33] op_sel_hi:[1,0,1]
	v_cvt_pk_f32_fp8_e32 v[42:43], v150
	v_cvt_pk_f32_fp8_sdwa v[44:45], v150 src0_sel:WORD_1
	v_pk_fma_f32 v[34:35], v[42:43], v[16:17], v[34:35] op_sel_hi:[1,0,1]
	v_pk_fma_f32 v[36:37], v[44:45], v[16:17], v[36:37] op_sel_hi:[1,0,1]
	v_cvt_pk_f32_fp8_e32 v[46:47], v151
	v_cvt_pk_f32_fp8_sdwa v[48:49], v151 src0_sel:WORD_1
	v_pk_fma_f32 v[38:39], v[46:47], v[16:17], v[38:39] op_sel_hi:[1,0,1]
	v_pk_fma_f32 v[40:41], v[48:49], v[16:17], v[40:41] op_sel_hi:[1,0,1]
	v_cvt_pk_f32_fp8_e32 v[42:43], v152
	v_cvt_pk_f32_fp8_sdwa v[44:45], v152 src0_sel:WORD_1
	v_pk_fma_f32 v[26:27], v[42:43], v[16:17], v[26:27] op_sel:[0,1,0] op_sel_hi:[1,1,1]
	v_pk_fma_f32 v[28:29], v[44:45], v[16:17], v[28:29] op_sel:[0,1,0] op_sel_hi:[1,1,1]
	v_cvt_pk_f32_fp8_e32 v[46:47], v153
	v_cvt_pk_f32_fp8_sdwa v[48:49], v153 src0_sel:WORD_1
	v_pk_fma_f32 v[30:31], v[46:47], v[16:17], v[30:31] op_sel:[0,1,0] op_sel_hi:[1,1,1]
	v_pk_fma_f32 v[32:33], v[48:49], v[16:17], v[32:33] op_sel:[0,1,0] op_sel_hi:[1,1,1]
	v_cvt_pk_f32_fp8_e32 v[42:43], v154
	v_cvt_pk_f32_fp8_sdwa v[44:45], v154 src0_sel:WORD_1
	v_pk_fma_f32 v[34:35], v[42:43], v[16:17], v[34:35] op_sel:[0,1,0] op_sel_hi:[1,1,1]
	v_pk_fma_f32 v[36:37], v[44:45], v[16:17], v[36:37] op_sel:[0,1,0] op_sel_hi:[1,1,1]
	v_cvt_pk_f32_fp8_e32 v[46:47], v155
	v_cvt_pk_f32_fp8_sdwa v[48:49], v155 src0_sel:WORD_1
	v_pk_fma_f32 v[38:39], v[46:47], v[16:17], v[38:39] op_sel:[0,1,0] op_sel_hi:[1,1,1]
	v_pk_fma_f32 v[40:41], v[48:49], v[16:17], v[40:41] op_sel:[0,1,0] op_sel_hi:[1,1,1]
	v_cvt_pk_f32_fp8_e32 v[42:43], v156
	v_cvt_pk_f32_fp8_sdwa v[44:45], v156 src0_sel:WORD_1
	v_pk_fma_f32 v[26:27], v[42:43], v[18:19], v[26:27] op_sel_hi:[1,0,1]
	v_pk_fma_f32 v[28:29], v[44:45], v[18:19], v[28:29] op_sel_hi:[1,0,1]
	v_cvt_pk_f32_fp8_e32 v[46:47], v157
	v_cvt_pk_f32_fp8_sdwa v[48:49], v157 src0_sel:WORD_1
	v_pk_fma_f32 v[30:31], v[46:47], v[18:19], v[30:31] op_sel_hi:[1,0,1]
	v_pk_fma_f32 v[32:33], v[48:49], v[18:19], v[32:33] op_sel_hi:[1,0,1]
	v_cvt_pk_f32_fp8_e32 v[42:43], v158
	v_cvt_pk_f32_fp8_sdwa v[44:45], v158 src0_sel:WORD_1
	v_pk_fma_f32 v[34:35], v[42:43], v[18:19], v[34:35] op_sel_hi:[1,0,1]
	v_pk_fma_f32 v[36:37], v[44:45], v[18:19], v[36:37] op_sel_hi:[1,0,1]
	v_cvt_pk_f32_fp8_e32 v[46:47], v159
	v_cvt_pk_f32_fp8_sdwa v[48:49], v159 src0_sel:WORD_1
	v_pk_fma_f32 v[38:39], v[46:47], v[18:19], v[38:39] op_sel_hi:[1,0,1]
	v_pk_fma_f32 v[40:41], v[48:49], v[18:19], v[40:41] op_sel_hi:[1,0,1]
	v_cvt_pk_f32_fp8_e32 v[42:43], v160
	v_cvt_pk_f32_fp8_sdwa v[44:45], v160 src0_sel:WORD_1
	v_pk_fma_f32 v[26:27], v[42:43], v[18:19], v[26:27] op_sel:[0,1,0] op_sel_hi:[1,1,1]
	v_pk_fma_f32 v[28:29], v[44:45], v[18:19], v[28:29] op_sel:[0,1,0] op_sel_hi:[1,1,1]
	v_cvt_pk_f32_fp8_e32 v[46:47], v161
	v_cvt_pk_f32_fp8_sdwa v[48:49], v161 src0_sel:WORD_1
	v_pk_fma_f32 v[30:31], v[46:47], v[18:19], v[30:31] op_sel:[0,1,0] op_sel_hi:[1,1,1]
	v_pk_fma_f32 v[32:33], v[48:49], v[18:19], v[32:33] op_sel:[0,1,0] op_sel_hi:[1,1,1]
	v_cvt_pk_f32_fp8_e32 v[42:43], v162
	v_cvt_pk_f32_fp8_sdwa v[44:45], v162 src0_sel:WORD_1
	v_pk_fma_f32 v[34:35], v[42:43], v[18:19], v[34:35] op_sel:[0,1,0] op_sel_hi:[1,1,1]
	v_pk_fma_f32 v[36:37], v[44:45], v[18:19], v[36:37] op_sel:[0,1,0] op_sel_hi:[1,1,1]
	v_cvt_pk_f32_fp8_e32 v[46:47], v163
	v_cvt_pk_f32_fp8_sdwa v[48:49], v163 src0_sel:WORD_1
	v_pk_fma_f32 v[38:39], v[46:47], v[18:19], v[38:39] op_sel:[0,1,0] op_sel_hi:[1,1,1]
	v_pk_fma_f32 v[40:41], v[48:49], v[18:19], v[40:41] op_sel:[0,1,0] op_sel_hi:[1,1,1]
	v_cvt_pk_f32_fp8_e32 v[42:43], v164
	v_cvt_pk_f32_fp8_sdwa v[44:45], v164 src0_sel:WORD_1
	v_pk_fma_f32 v[26:27], v[42:43], v[20:21], v[26:27] op_sel_hi:[1,0,1]
	v_pk_fma_f32 v[28:29], v[44:45], v[20:21], v[28:29] op_sel_hi:[1,0,1]
	v_cvt_pk_f32_fp8_e32 v[46:47], v165
	v_cvt_pk_f32_fp8_sdwa v[48:49], v165 src0_sel:WORD_1
	v_pk_fma_f32 v[30:31], v[46:47], v[20:21], v[30:31] op_sel_hi:[1,0,1]
	v_pk_fma_f32 v[32:33], v[48:49], v[20:21], v[32:33] op_sel_hi:[1,0,1]
	v_cvt_pk_f32_fp8_e32 v[42:43], v166
	v_cvt_pk_f32_fp8_sdwa v[44:45], v166 src0_sel:WORD_1
	v_pk_fma_f32 v[34:35], v[42:43], v[20:21], v[34:35] op_sel_hi:[1,0,1]
	v_pk_fma_f32 v[36:37], v[44:45], v[20:21], v[36:37] op_sel_hi:[1,0,1]
	v_cvt_pk_f32_fp8_e32 v[46:47], v167
	v_cvt_pk_f32_fp8_sdwa v[48:49], v167 src0_sel:WORD_1
	v_pk_fma_f32 v[38:39], v[46:47], v[20:21], v[38:39] op_sel_hi:[1,0,1]
	v_pk_fma_f32 v[40:41], v[48:49], v[20:21], v[40:41] op_sel_hi:[1,0,1]
	v_cvt_pk_f32_fp8_e32 v[42:43], v168
	v_cvt_pk_f32_fp8_sdwa v[44:45], v168 src0_sel:WORD_1
	v_pk_fma_f32 v[26:27], v[42:43], v[20:21], v[26:27] op_sel:[0,1,0] op_sel_hi:[1,1,1]
	v_pk_fma_f32 v[28:29], v[44:45], v[20:21], v[28:29] op_sel:[0,1,0] op_sel_hi:[1,1,1]
	v_cvt_pk_f32_fp8_e32 v[46:47], v169
	v_cvt_pk_f32_fp8_sdwa v[48:49], v169 src0_sel:WORD_1
	v_pk_fma_f32 v[30:31], v[46:47], v[20:21], v[30:31] op_sel:[0,1,0] op_sel_hi:[1,1,1]
	v_pk_fma_f32 v[32:33], v[48:49], v[20:21], v[32:33] op_sel:[0,1,0] op_sel_hi:[1,1,1]
	v_cvt_pk_f32_fp8_e32 v[42:43], v170
	v_cvt_pk_f32_fp8_sdwa v[44:45], v170 src0_sel:WORD_1
	v_pk_fma_f32 v[34:35], v[42:43], v[20:21], v[34:35] op_sel:[0,1,0] op_sel_hi:[1,1,1]
	v_pk_fma_f32 v[36:37], v[44:45], v[20:21], v[36:37] op_sel:[0,1,0] op_sel_hi:[1,1,1]
	v_cvt_pk_f32_fp8_e32 v[46:47], v171
	v_cvt_pk_f32_fp8_sdwa v[48:49], v171 src0_sel:WORD_1
	v_pk_fma_f32 v[38:39], v[46:47], v[20:21], v[38:39] op_sel:[0,1,0] op_sel_hi:[1,1,1]
	v_pk_fma_f32 v[40:41], v[48:49], v[20:21], v[40:41] op_sel:[0,1,0] op_sel_hi:[1,1,1]
	v_cvt_pk_f32_fp8_e32 v[42:43], v172
	v_cvt_pk_f32_fp8_sdwa v[44:45], v172 src0_sel:WORD_1
	v_pk_fma_f32 v[26:27], v[42:43], v[22:23], v[26:27] op_sel_hi:[1,0,1]
	v_pk_fma_f32 v[28:29], v[44:45], v[22:23], v[28:29] op_sel_hi:[1,0,1]
	v_cvt_pk_f32_fp8_e32 v[46:47], v173
	v_cvt_pk_f32_fp8_sdwa v[48:49], v173 src0_sel:WORD_1
	v_pk_fma_f32 v[30:31], v[46:47], v[22:23], v[30:31] op_sel_hi:[1,0,1]
	v_pk_fma_f32 v[32:33], v[48:49], v[22:23], v[32:33] op_sel_hi:[1,0,1]
	v_cvt_pk_f32_fp8_e32 v[42:43], v174
	v_cvt_pk_f32_fp8_sdwa v[44:45], v174 src0_sel:WORD_1
	v_pk_fma_f32 v[34:35], v[42:43], v[22:23], v[34:35] op_sel_hi:[1,0,1]
	v_pk_fma_f32 v[36:37], v[44:45], v[22:23], v[36:37] op_sel_hi:[1,0,1]
	v_cvt_pk_f32_fp8_e32 v[46:47], v175
	v_cvt_pk_f32_fp8_sdwa v[48:49], v175 src0_sel:WORD_1
	v_pk_fma_f32 v[38:39], v[46:47], v[22:23], v[38:39] op_sel_hi:[1,0,1]
	v_pk_fma_f32 v[40:41], v[48:49], v[22:23], v[40:41] op_sel_hi:[1,0,1]
	v_cvt_pk_f32_fp8_e32 v[42:43], v176
	v_cvt_pk_f32_fp8_sdwa v[44:45], v176 src0_sel:WORD_1
	v_pk_fma_f32 v[26:27], v[42:43], v[22:23], v[26:27] op_sel:[0,1,0] op_sel_hi:[1,1,1]
	v_pk_fma_f32 v[28:29], v[44:45], v[22:23], v[28:29] op_sel:[0,1,0] op_sel_hi:[1,1,1]
	v_cvt_pk_f32_fp8_e32 v[46:47], v177
	v_cvt_pk_f32_fp8_sdwa v[48:49], v177 src0_sel:WORD_1
	v_pk_fma_f32 v[30:31], v[46:47], v[22:23], v[30:31] op_sel:[0,1,0] op_sel_hi:[1,1,1]
	v_pk_fma_f32 v[32:33], v[48:49], v[22:23], v[32:33] op_sel:[0,1,0] op_sel_hi:[1,1,1]
	v_cvt_pk_f32_fp8_e32 v[42:43], v178
	v_cvt_pk_f32_fp8_sdwa v[44:45], v178 src0_sel:WORD_1
	v_pk_fma_f32 v[34:35], v[42:43], v[22:23], v[34:35] op_sel:[0,1,0] op_sel_hi:[1,1,1]
	v_pk_fma_f32 v[36:37], v[44:45], v[22:23], v[36:37] op_sel:[0,1,0] op_sel_hi:[1,1,1]
	v_cvt_pk_f32_fp8_e32 v[46:47], v179
	v_cvt_pk_f32_fp8_sdwa v[48:49], v179 src0_sel:WORD_1
	v_pk_fma_f32 v[38:39], v[46:47], v[22:23], v[38:39] op_sel:[0,1,0] op_sel_hi:[1,1,1]
	v_pk_fma_f32 v[40:41], v[48:49], v[22:23], v[40:41] op_sel:[0,1,0] op_sel_hi:[1,1,1]
	v_cvt_pk_f32_fp8_e32 v[42:43], v180
	v_cvt_pk_f32_fp8_sdwa v[44:45], v180 src0_sel:WORD_1
	v_pk_fma_f32 v[26:27], v[42:43], v[24:25], v[26:27] op_sel_hi:[1,0,1]
	v_pk_fma_f32 v[28:29], v[44:45], v[24:25], v[28:29] op_sel_hi:[1,0,1]
	v_cvt_pk_f32_fp8_e32 v[46:47], v181
	v_cvt_pk_f32_fp8_sdwa v[48:49], v181 src0_sel:WORD_1
	v_pk_fma_f32 v[30:31], v[46:47], v[24:25], v[30:31] op_sel_hi:[1,0,1]
	v_pk_fma_f32 v[32:33], v[48:49], v[24:25], v[32:33] op_sel_hi:[1,0,1]
	v_cvt_pk_f32_fp8_e32 v[42:43], v182
	v_cvt_pk_f32_fp8_sdwa v[44:45], v182 src0_sel:WORD_1
	v_pk_fma_f32 v[34:35], v[42:43], v[24:25], v[34:35] op_sel_hi:[1,0,1]
	v_pk_fma_f32 v[36:37], v[44:45], v[24:25], v[36:37] op_sel_hi:[1,0,1]
	v_cvt_pk_f32_fp8_e32 v[46:47], v183
	v_cvt_pk_f32_fp8_sdwa v[48:49], v183 src0_sel:WORD_1
	v_pk_fma_f32 v[38:39], v[46:47], v[24:25], v[38:39] op_sel_hi:[1,0,1]
	v_pk_fma_f32 v[40:41], v[48:49], v[24:25], v[40:41] op_sel_hi:[1,0,1]
; __device__ __forceinline__ float wsum(float v) { v = dpp_row_sum16(v); v += __shfl_xor(v, 16); v += __shfl_xor(v, 32); return v; }
; #define P5_LOAD(A, TAB, j0)                                                                \
;   _Pragma("unroll") for (int q = 0; q < 16; q++) {                                         \
;     A[q] = ((const uint4*)((TAB) + (size_t)widx[(j0) + q] * 1024))[lane];                  \
;   }
; __device__ __forceinline__ void phase5(const Params& p, char* smem, const bool store_x = true) {
;     ...
; #pragma unroll 1
;     for (int j0 = 0; j0 < 128; j0 += 32) {
;       P5_LOAD(A1, EV, j0 + 16)
;       P5_COMPUTE_V(A0, j0)
;       if (j0 + 32 < 128) { P5_LOAD(A0, EV, j0 + 32) }
;       P5_COMPUTE_V(A1, j0 + 16)
;     }
;     float x2[16];
; #pragma unroll
;     for (int i = 0; i < 4; i++) {
;       const float4 xv = i == 0 ? xv0 : i == 1 ? xv1 : i == 2 ? xv2 : xv3;
;       x2[4 * i] = xv.x + o2[2 * i].x; x2[4 * i + 1] = xv.y + o2[2 * i].y; x2[4 * i + 2] = xv.z + o2[2 * i + 1].x; x2[4 * i + 3] = xv.w + o2[2 * i + 1].y;
;     }
;     float ss = 0.f;
; #pragma unroll
;     for (int i = 0; i < 16; i++) ss += x2[i] * x2[i];
;     ss = wsum(ss);
;     const float rs = rsqrtf(ss * (1.f / 1024.f) + EPSF);
;     if (store_x) {
; #pragma unroll
;       for (int i = 0; i < 4; i++) *(float4*)(xr + i * 4) = make_float4(x2[4 * i], x2[4 * i + 1], x2[4 * i + 2], x2[4 * i + 3]);
;     }
	v_cvt_pk_f32_fp8_e32 v[42:43], v184
	v_cvt_pk_f32_fp8_sdwa v[44:45], v184 src0_sel:WORD_1
	v_pk_fma_f32 v[26:27], v[42:43], v[24:25], v[26:27] op_sel:[0,1,0] op_sel_hi:[1,1,1]
	v_pk_fma_f32 v[28:29], v[44:45], v[24:25], v[28:29] op_sel:[0,1,0] op_sel_hi:[1,1,1]
	v_cvt_pk_f32_fp8_e32 v[46:47], v185
	v_cvt_pk_f32_fp8_sdwa v[48:49], v185 src0_sel:WORD_1
	v_pk_fma_f32 v[30:31], v[46:47], v[24:25], v[30:31] op_sel:[0,1,0] op_sel_hi:[1,1,1]
	v_pk_fma_f32 v[32:33], v[48:49], v[24:25], v[32:33] op_sel:[0,1,0] op_sel_hi:[1,1,1]
	v_cvt_pk_f32_fp8_e32 v[42:43], v186
	v_cvt_pk_f32_fp8_sdwa v[44:45], v186 src0_sel:WORD_1
	v_pk_fma_f32 v[34:35], v[42:43], v[24:25], v[34:35] op_sel:[0,1,0] op_sel_hi:[1,1,1]
	v_pk_fma_f32 v[36:37], v[44:45], v[24:25], v[36:37] op_sel:[0,1,0] op_sel_hi:[1,1,1]
	v_cvt_pk_f32_fp8_e32 v[46:47], v187
	v_cvt_pk_f32_fp8_sdwa v[48:49], v187 src0_sel:WORD_1
	v_pk_fma_f32 v[38:39], v[46:47], v[24:25], v[38:39] op_sel:[0,1,0] op_sel_hi:[1,1,1]
	v_pk_fma_f32 v[40:41], v[48:49], v[24:25], v[40:41] op_sel:[0,1,0] op_sel_hi:[1,1,1]
	s_nop 1
	v_permlane32_swap_b32_e32 v26, v34
	v_permlane32_swap_b32_e32 v27, v35
	v_permlane32_swap_b32_e32 v28, v36
	v_permlane32_swap_b32_e32 v29, v37
	v_permlane32_swap_b32_e32 v30, v38
	v_permlane32_swap_b32_e32 v31, v39
	v_permlane32_swap_b32_e32 v32, v40
	v_permlane32_swap_b32_e32 v33, v41
	v_add_f32_e32 v26, v26, v34
	v_add_f32_e32 v27, v27, v35
	v_add_f32_e32 v28, v28, v36
	v_add_f32_e32 v29, v29, v37
	v_add_f32_e32 v30, v30, v38
	v_add_f32_e32 v31, v31, v39
	v_add_f32_e32 v32, v32, v40
	v_add_f32_e32 v33, v33, v41
	s_nop 1
	v_permlane16_swap_b32_e32 v26, v30
	v_permlane16_swap_b32_e32 v27, v31
	v_permlane16_swap_b32_e32 v28, v32
	v_permlane16_swap_b32_e32 v29, v33
	v_add_f32_e32 v26, v26, v30
	v_add_f32_e32 v27, v27, v31
	v_add_f32_e32 v28, v28, v32
	v_add_f32_e32 v29, v29, v33
	s_lshl_b32 s11, s12, 12
	v_add_u32_e32 v6, s11, v3
	v_add_f32_dpp v42, v26, v26 row_ror:8 row_mask:0xf bank_mask:0xf
	v_add_f32_dpp v43, v28, v28 row_ror:8 row_mask:0xf bank_mask:0xf
	v_add_f32_dpp v44, v27, v27 row_ror:8 row_mask:0xf bank_mask:0xf
	v_add_f32_dpp v45, v29, v29 row_ror:8 row_mask:0xf bank_mask:0xf
	v_cndmask_b32_e64 v46, v42, v43, s[14:15]
	v_cndmask_b32_e64 v47, v44, v45, s[14:15]
	v_add_f32_e32 v46, v52, v46
	v_add_f32_e32 v47, v53, v47
	global_store_dwordx2 v6, v[46:47], s[6:7]
	v_mul_f32_e32 v48, v46, v46
	v_fmac_f32_e32 v48, v47, v47
	s_lshl_b32 s11, s12, 2
	s_add_u32 s11, s11, 0x1100000
	v_mov_b32_e32 v7, s11
	v_add_f32_dpp v48, v48, v48 quad_perm:[1,0,3,2] row_mask:0xf bank_mask:0xf
	s_nop 1
	v_add_f32_dpp v48, v48, v48 quad_perm:[2,3,0,1] row_mask:0xf bank_mask:0xf
	s_nop 1
	v_add_f32_dpp v48, v48, v48 row_half_mirror row_mask:0xf bank_mask:0xf
	s_nop 1
	v_add_f32_dpp v48, v48, v48 row_mirror row_mask:0xf bank_mask:0xf
	s_nop 1
	v_add_f32_dpp v48, v48, v48 row_bcast:15 row_mask:0xa bank_mask:0xf
	s_nop 1
	v_add_f32_dpp v48, v48, v48 row_bcast:31 row_mask:0xc bank_mask:0xf
	s_nop 1
	s_mov_b32 exec_lo, 0
	s_brev_b32 exec_hi, 1
	global_atomic_add_f32 v7, v48, s[4:5]
	s_mov_b64 exec, -1
.Lp5v_skip1:
	s_add_u32 s10, s8, s29
	s_min_u32 s10, s10, s13
	s_lshl_b32 s18, s10, 10
	s_add_u32 s11, s16, 10
	s_and_b32 s11, s11, 15
	s_lshl_b32 s11, s11, 10
	s_add_u32 s11, s11, s17
	s_mov_b32 m0, s11
	v_lshl_add_u64 v[4:5], v[58:59], 0, s[18:19]
	global_load_lds_dwordx4 v[4:5], off
	s_add_u32 s11, s16, 5
	s_and_b32 s11, s11, 15
	s_lshl_b32 s11, s11, 10
	v_add_u32_e32 v8, s11, v2
	ds_read_b128 v[10:13], v8 offset:0
	ds_read_b128 v[14:17], v8 offset:16
	ds_read_b128 v[18:21], v8 offset:32
	ds_read_b128 v[22:25], v8 offset:48
	s_add_u32 s10, s8, s24
	s_min_u32 s10, s10, s13
	s_lshl_b32 s11, s10, 12
	v_add_u32_e32 v6, s11, v3
	global_load_dwordx2 v[52:53], v6, s[6:7]
	s_waitcnt lgkmcnt(0)
	v_add_u32_e32 v10, v10, v1
	global_load_dwordx4 v[124:127], v10, s[2:3]
	v_add_u32_e32 v11, v11, v1
	global_load_dwordx4 v[128:131], v11, s[2:3]
	v_add_u32_e32 v12, v12, v1
	global_load_dwordx4 v[132:135], v12, s[2:3]
	v_add_u32_e32 v13, v13, v1
	global_load_dwordx4 v[136:139], v13, s[2:3]
	v_add_u32_e32 v14, v14, v1
	global_load_dwordx4 v[140:143], v14, s[2:3]
	v_add_u32_e32 v15, v15, v1
	global_load_dwordx4 v[144:147], v15, s[2:3]
	v_add_u32_e32 v16, v16, v1
	global_load_dwordx4 v[148:151], v16, s[2:3]
	v_add_u32_e32 v17, v17, v1
	global_load_dwordx4 v[152:155], v17, s[2:3]
	v_add_u32_e32 v18, v18, v1
	global_load_dwordx4 v[156:159], v18, s[2:3]
	v_add_u32_e32 v19, v19, v1
	global_load_dwordx4 v[160:163], v19, s[2:3]
	v_add_u32_e32 v20, v20, v1
	global_load_dwordx4 v[164:167], v20, s[2:3]
	v_add_u32_e32 v21, v21, v1
	global_load_dwordx4 v[168:171], v21, s[2:3]
	v_add_u32_e32 v22, v22, v1
	global_load_dwordx4 v[172:175], v22, s[2:3]
	v_add_u32_e32 v23, v23, v1
	global_load_dwordx4 v[176:179], v23, s[2:3]
	v_add_u32_e32 v24, v24, v1
	global_load_dwordx4 v[180:183], v24, s[2:3]
	v_add_u32_e32 v25, v25, v1
	global_load_dwordx4 v[184:187], v25, s[2:3]
	s_add_u32 s11, s16, 2
	s_and_b32 s11, s11, 15
	s_lshl_b32 s11, s11, 10
	v_add_u32_e32 v8, s11, v2
	ds_read_b128 v[10:13], v8 offset:512
	ds_read_b128 v[14:17], v8 offset:528
	ds_read_b128 v[18:21], v8 offset:544
	ds_read_b128 v[22:25], v8 offset:560
	s_add_u32 s12, s8, s21
	s_waitcnt vmcnt(60) lgkmcnt(0)
	s_cmp_lt_u32 s12, 0x4200
	s_cbranch_scc0 .Lp5v_skip2
	v_cvt_pk_f32_fp8_e32 v[42:43], v188
	v_cvt_pk_f32_fp8_sdwa v[44:45], v188 src0_sel:WORD_1
	v_pk_mul_f32 v[26:27], v[42:43], v[10:11] op_sel_hi:[1,0]
	v_pk_mul_f32 v[28:29], v[44:45], v[10:11] op_sel_hi:[1,0]
	v_cvt_pk_f32_fp8_e32 v[46:47], v189
	v_cvt_pk_f32_fp8_sdwa v[48:49], v189 src0_sel:WORD_1
	v_pk_mul_f32 v[30:31], v[46:47], v[10:11] op_sel_hi:[1,0]
	v_pk_mul_f32 v[32:33], v[48:49], v[10:11] op_sel_hi:[1,0]
	v_cvt_pk_f32_fp8_e32 v[42:43], v190
	v_cvt_pk_f32_fp8_sdwa v[44:45], v190 src0_sel:WORD_1
	v_pk_mul_f32 v[34:35], v[42:43], v[10:11] op_sel_hi:[1,0]
	v_pk_mul_f32 v[36:37], v[44:45], v[10:11] op_sel_hi:[1,0]
	v_cvt_pk_f32_fp8_e32 v[46:47], v191
	v_cvt_pk_f32_fp8_sdwa v[48:49], v191 src0_sel:WORD_1
	v_pk_mul_f32 v[38:39], v[46:47], v[10:11] op_sel_hi:[1,0]
	v_pk_mul_f32 v[40:41], v[48:49], v[10:11] op_sel_hi:[1,0]
	v_cvt_pk_f32_fp8_e32 v[42:43], v192
	v_cvt_pk_f32_fp8_sdwa v[44:45], v192 src0_sel:WORD_1
	v_pk_fma_f32 v[26:27], v[42:43], v[10:11], v[26:27] op_sel:[0,1,0] op_sel_hi:[1,1,1]
	v_pk_fma_f32 v[28:29], v[44:45], v[10:11], v[28:29] op_sel:[0,1,0] op_sel_hi:[1,1,1]
	v_cvt_pk_f32_fp8_e32 v[46:47], v193
	v_cvt_pk_f32_fp8_sdwa v[48:49], v193 src0_sel:WORD_1
	v_pk_fma_f32 v[30:31], v[46:47], v[10:11], v[30:31] op_sel:[0,1,0] op_sel_hi:[1,1,1]
	v_pk_fma_f32 v[32:33], v[48:49], v[10:11], v[32:33] op_sel:[0,1,0] op_sel_hi:[1,1,1]
	v_cvt_pk_f32_fp8_e32 v[42:43], v194
	v_cvt_pk_f32_fp8_sdwa v[44:45], v194 src0_sel:WORD_1
	v_pk_fma_f32 v[34:35], v[42:43], v[10:11], v[34:35] op_sel:[0,1,0] op_sel_hi:[1,1,1]
	v_pk_fma_f32 v[36:37], v[44:45], v[10:11], v[36:37] op_sel:[0,1,0] op_sel_hi:[1,1,1]
	v_cvt_pk_f32_fp8_e32 v[46:47], v195
	v_cvt_pk_f32_fp8_sdwa v[48:49], v195 src0_sel:WORD_1
	v_pk_fma_f32 v[38:39], v[46:47], v[10:11], v[38:39] op_sel:[0,1,0] op_sel_hi:[1,1,1]
	v_pk_fma_f32 v[40:41], v[48:49], v[10:11], v[40:41] op_sel:[0,1,0] op_sel_hi:[1,1,1]
	v_cvt_pk_f32_fp8_e32 v[42:43], v196
	v_cvt_pk_f32_fp8_sdwa v[44:45], v196 src0_sel:WORD_1
	v_pk_fma_f32 v[26:27], v[42:43], v[12:13], v[26:27] op_sel_hi:[1,0,1]
	v_pk_fma_f32 v[28:29], v[44:45], v[12:13], v[28:29] op_sel_hi:[1,0,1]
	v_cvt_pk_f32_fp8_e32 v[46:47], v197
	v_cvt_pk_f32_fp8_sdwa v[48:49], v197 src0_sel:WORD_1
	v_pk_fma_f32 v[30:31], v[46:47], v[12:13], v[30:31] op_sel_hi:[1,0,1]
	v_pk_fma_f32 v[32:33], v[48:49], v[12:13], v[32:33] op_sel_hi:[1,0,1]
	v_cvt_pk_f32_fp8_e32 v[42:43], v198
	v_cvt_pk_f32_fp8_sdwa v[44:45], v198 src0_sel:WORD_1
	v_pk_fma_f32 v[34:35], v[42:43], v[12:13], v[34:35] op_sel_hi:[1,0,1]
	v_pk_fma_f32 v[36:37], v[44:45], v[12:13], v[36:37] op_sel_hi:[1,0,1]
	v_cvt_pk_f32_fp8_e32 v[46:47], v199
	v_cvt_pk_f32_fp8_sdwa v[48:49], v199 src0_sel:WORD_1
	v_pk_fma_f32 v[38:39], v[46:47], v[12:13], v[38:39] op_sel_hi:[1,0,1]
	v_pk_fma_f32 v[40:41], v[48:49], v[12:13], v[40:41] op_sel_hi:[1,0,1]
	v_cvt_pk_f32_fp8_e32 v[42:43], v200
	v_cvt_pk_f32_fp8_sdwa v[44:45], v200 src0_sel:WORD_1
	v_pk_fma_f32 v[26:27], v[42:43], v[12:13], v[26:27] op_sel:[0,1,0] op_sel_hi:[1,1,1]
	v_pk_fma_f32 v[28:29], v[44:45], v[12:13], v[28:29] op_sel:[0,1,0] op_sel_hi:[1,1,1]
	v_cvt_pk_f32_fp8_e32 v[46:47], v201
	v_cvt_pk_f32_fp8_sdwa v[48:49], v201 src0_sel:WORD_1
	v_pk_fma_f32 v[30:31], v[46:47], v[12:13], v[30:31] op_sel:[0,1,0] op_sel_hi:[1,1,1]
	v_pk_fma_f32 v[32:33], v[48:49], v[12:13], v[32:33] op_sel:[0,1,0] op_sel_hi:[1,1,1]
	v_cvt_pk_f32_fp8_e32 v[42:43], v202
	v_cvt_pk_f32_fp8_sdwa v[44:45], v202 src0_sel:WORD_1
	v_pk_fma_f32 v[34:35], v[42:43], v[12:13], v[34:35] op_sel:[0,1,0] op_sel_hi:[1,1,1]
	v_pk_fma_f32 v[36:37], v[44:45], v[12:13], v[36:37] op_sel:[0,1,0] op_sel_hi:[1,1,1]
	v_cvt_pk_f32_fp8_e32 v[46:47], v203
	v_cvt_pk_f32_fp8_sdwa v[48:49], v203 src0_sel:WORD_1
	v_pk_fma_f32 v[38:39], v[46:47], v[12:13], v[38:39] op_sel:[0,1,0] op_sel_hi:[1,1,1]
	v_pk_fma_f32 v[40:41], v[48:49], v[12:13], v[40:41] op_sel:[0,1,0] op_sel_hi:[1,1,1]
	v_cvt_pk_f32_fp8_e32 v[42:43], v204
	v_cvt_pk_f32_fp8_sdwa v[44:45], v204 src0_sel:WORD_1
	v_pk_fma_f32 v[26:27], v[42:43], v[14:15], v[26:27] op_sel_hi:[1,0,1]
	v_pk_fma_f32 v[28:29], v[44:45], v[14:15], v[28:29] op_sel_hi:[1,0,1]
	v_cvt_pk_f32_fp8_e32 v[46:47], v205
	v_cvt_pk_f32_fp8_sdwa v[48:49], v205 src0_sel:WORD_1
	v_pk_fma_f32 v[30:31], v[46:47], v[14:15], v[30:31] op_sel_hi:[1,0,1]
	v_pk_fma_f32 v[32:33], v[48:49], v[14:15], v[32:33] op_sel_hi:[1,0,1]
	v_cvt_pk_f32_fp8_e32 v[42:43], v206
	v_cvt_pk_f32_fp8_sdwa v[44:45], v206 src0_sel:WORD_1
	v_pk_fma_f32 v[34:35], v[42:43], v[14:15], v[34:35] op_sel_hi:[1,0,1]
	v_pk_fma_f32 v[36:37], v[44:45], v[14:15], v[36:37] op_sel_hi:[1,0,1]
	v_cvt_pk_f32_fp8_e32 v[46:47], v207
	v_cvt_pk_f32_fp8_sdwa v[48:49], v207 src0_sel:WORD_1
	v_pk_fma_f32 v[38:39], v[46:47], v[14:15], v[38:39] op_sel_hi:[1,0,1]
	v_pk_fma_f32 v[40:41], v[48:49], v[14:15], v[40:41] op_sel_hi:[1,0,1]
	v_cvt_pk_f32_fp8_e32 v[42:43], v208
	v_cvt_pk_f32_fp8_sdwa v[44:45], v208 src0_sel:WORD_1
	v_pk_fma_f32 v[26:27], v[42:43], v[14:15], v[26:27] op_sel:[0,1,0] op_sel_hi:[1,1,1]
	v_pk_fma_f32 v[28:29], v[44:45], v[14:15], v[28:29] op_sel:[0,1,0] op_sel_hi:[1,1,1]
	v_cvt_pk_f32_fp8_e32 v[46:47], v209
	v_cvt_pk_f32_fp8_sdwa v[48:49], v209 src0_sel:WORD_1
	v_pk_fma_f32 v[30:31], v[46:47], v[14:15], v[30:31] op_sel:[0,1,0] op_sel_hi:[1,1,1]
	v_pk_fma_f32 v[32:33], v[48:49], v[14:15], v[32:33] op_sel:[0,1,0] op_sel_hi:[1,1,1]
	v_cvt_pk_f32_fp8_e32 v[42:43], v210
	v_cvt_pk_f32_fp8_sdwa v[44:45], v210 src0_sel:WORD_1
	v_pk_fma_f32 v[34:35], v[42:43], v[14:15], v[34:35] op_sel:[0,1,0] op_sel_hi:[1,1,1]
	v_pk_fma_f32 v[36:37], v[44:45], v[14:15], v[36:37] op_sel:[0,1,0] op_sel_hi:[1,1,1]
	v_cvt_pk_f32_fp8_e32 v[46:47], v211
	v_cvt_pk_f32_fp8_sdwa v[48:49], v211 src0_sel:WORD_1
	v_pk_fma_f32 v[38:39], v[46:47], v[14:15], v[38:39] op_sel:[0,1,0] op_sel_hi:[1,1,1]
	v_pk_fma_f32 v[40:41], v[48:49], v[14:15], v[40:41] op_sel:[0,1,0] op_sel_hi:[1,1,1]
	v_cvt_pk_f32_fp8_e32 v[42:43], v212
	v_cvt_pk_f32_fp8_sdwa v[44:45], v212 src0_sel:WORD_1
	v_pk_fma_f32 v[26:27], v[42:43], v[16:17], v[26:27] op_sel_hi:[1,0,1]
	v_pk_fma_f32 v[28:29], v[44:45], v[16:17], v[28:29] op_sel_hi:[1,0,1]
	v_cvt_pk_f32_fp8_e32 v[46:47], v213
	v_cvt_pk_f32_fp8_sdwa v[48:49], v213 src0_sel:WORD_1
	v_pk_fma_f32 v[30:31], v[46:47], v[16:17], v[30:31] op_sel_hi:[1,0,1]
	v_pk_fma_f32 v[32:33], v[48:49], v[16:17], v[32:33] op_sel_hi:[1,0,1]
	v_cvt_pk_f32_fp8_e32 v[42:43], v214
	v_cvt_pk_f32_fp8_sdwa v[44:45], v214 src0_sel:WORD_1
	v_pk_fma_f32 v[34:35], v[42:43], v[16:17], v[34:35] op_sel_hi:[1,0,1]
	v_pk_fma_f32 v[36:37], v[44:45], v[16:17], v[36:37] op_sel_hi:[1,0,1]
	v_cvt_pk_f32_fp8_e32 v[46:47], v215
	v_cvt_pk_f32_fp8_sdwa v[48:49], v215 src0_sel:WORD_1
	v_pk_fma_f32 v[38:39], v[46:47], v[16:17], v[38:39] op_sel_hi:[1,0,1]
	v_pk_fma_f32 v[40:41], v[48:49], v[16:17], v[40:41] op_sel_hi:[1,0,1]
	v_cvt_pk_f32_fp8_e32 v[42:43], v216
	v_cvt_pk_f32_fp8_sdwa v[44:45], v216 src0_sel:WORD_1
	v_pk_fma_f32 v[26:27], v[42:43], v[16:17], v[26:27] op_sel:[0,1,0] op_sel_hi:[1,1,1]
	v_pk_fma_f32 v[28:29], v[44:45], v[16:17], v[28:29] op_sel:[0,1,0] op_sel_hi:[1,1,1]
	v_cvt_pk_f32_fp8_e32 v[46:47], v217
	v_cvt_pk_f32_fp8_sdwa v[48:49], v217 src0_sel:WORD_1
	v_pk_fma_f32 v[30:31], v[46:47], v[16:17], v[30:31] op_sel:[0,1,0] op_sel_hi:[1,1,1]
	v_pk_fma_f32 v[32:33], v[48:49], v[16:17], v[32:33] op_sel:[0,1,0] op_sel_hi:[1,1,1]
	v_cvt_pk_f32_fp8_e32 v[42:43], v218
	v_cvt_pk_f32_fp8_sdwa v[44:45], v218 src0_sel:WORD_1
	v_pk_fma_f32 v[34:35], v[42:43], v[16:17], v[34:35] op_sel:[0,1,0] op_sel_hi:[1,1,1]
	v_pk_fma_f32 v[36:37], v[44:45], v[16:17], v[36:37] op_sel:[0,1,0] op_sel_hi:[1,1,1]
	v_cvt_pk_f32_fp8_e32 v[46:47], v219
	v_cvt_pk_f32_fp8_sdwa v[48:49], v219 src0_sel:WORD_1
	v_pk_fma_f32 v[38:39], v[46:47], v[16:17], v[38:39] op_sel:[0,1,0] op_sel_hi:[1,1,1]
	v_pk_fma_f32 v[40:41], v[48:49], v[16:17], v[40:41] op_sel:[0,1,0] op_sel_hi:[1,1,1]
	v_cvt_pk_f32_fp8_e32 v[42:43], v220
	v_cvt_pk_f32_fp8_sdwa v[44:45], v220 src0_sel:WORD_1
	v_pk_fma_f32 v[26:27], v[42:43], v[18:19], v[26:27] op_sel_hi:[1,0,1]
	v_pk_fma_f32 v[28:29], v[44:45], v[18:19], v[28:29] op_sel_hi:[1,0,1]
	v_cvt_pk_f32_fp8_e32 v[46:47], v221
	v_cvt_pk_f32_fp8_sdwa v[48:49], v221 src0_sel:WORD_1
	v_pk_fma_f32 v[30:31], v[46:47], v[18:19], v[30:31] op_sel_hi:[1,0,1]
	v_pk_fma_f32 v[32:33], v[48:49], v[18:19], v[32:33] op_sel_hi:[1,0,1]
	v_cvt_pk_f32_fp8_e32 v[42:43], v222
	v_cvt_pk_f32_fp8_sdwa v[44:45], v222 src0_sel:WORD_1
	v_pk_fma_f32 v[34:35], v[42:43], v[18:19], v[34:35] op_sel_hi:[1,0,1]
	v_pk_fma_f32 v[36:37], v[44:45], v[18:19], v[36:37] op_sel_hi:[1,0,1]
	v_cvt_pk_f32_fp8_e32 v[46:47], v223
	v_cvt_pk_f32_fp8_sdwa v[48:49], v223 src0_sel:WORD_1
	v_pk_fma_f32 v[38:39], v[46:47], v[18:19], v[38:39] op_sel_hi:[1,0,1]
	v_pk_fma_f32 v[40:41], v[48:49], v[18:19], v[40:41] op_sel_hi:[1,0,1]
	v_cvt_pk_f32_fp8_e32 v[42:43], v224
	v_cvt_pk_f32_fp8_sdwa v[44:45], v224 src0_sel:WORD_1
	v_pk_fma_f32 v[26:27], v[42:43], v[18:19], v[26:27] op_sel:[0,1,0] op_sel_hi:[1,1,1]
	v_pk_fma_f32 v[28:29], v[44:45], v[18:19], v[28:29] op_sel:[0,1,0] op_sel_hi:[1,1,1]
	v_cvt_pk_f32_fp8_e32 v[46:47], v225
	v_cvt_pk_f32_fp8_sdwa v[48:49], v225 src0_sel:WORD_1
	v_pk_fma_f32 v[30:31], v[46:47], v[18:19], v[30:31] op_sel:[0,1,0] op_sel_hi:[1,1,1]
	v_pk_fma_f32 v[32:33], v[48:49], v[18:19], v[32:33] op_sel:[0,1,0] op_sel_hi:[1,1,1]
	v_cvt_pk_f32_fp8_e32 v[42:43], v226
	v_cvt_pk_f32_fp8_sdwa v[44:45], v226 src0_sel:WORD_1
	v_pk_fma_f32 v[34:35], v[42:43], v[18:19], v[34:35] op_sel:[0,1,0] op_sel_hi:[1,1,1]
	v_pk_fma_f32 v[36:37], v[44:45], v[18:19], v[36:37] op_sel:[0,1,0] op_sel_hi:[1,1,1]
	v_cvt_pk_f32_fp8_e32 v[46:47], v227
	v_cvt_pk_f32_fp8_sdwa v[48:49], v227 src0_sel:WORD_1
	v_pk_fma_f32 v[38:39], v[46:47], v[18:19], v[38:39] op_sel:[0,1,0] op_sel_hi:[1,1,1]
	v_pk_fma_f32 v[40:41], v[48:49], v[18:19], v[40:41] op_sel:[0,1,0] op_sel_hi:[1,1,1]
	v_cvt_pk_f32_fp8_e32 v[42:43], v228
	v_cvt_pk_f32_fp8_sdwa v[44:45], v228 src0_sel:WORD_1
	v_pk_fma_f32 v[26:27], v[42:43], v[20:21], v[26:27] op_sel_hi:[1,0,1]
	v_pk_fma_f32 v[28:29], v[44:45], v[20:21], v[28:29] op_sel_hi:[1,0,1]
	v_cvt_pk_f32_fp8_e32 v[46:47], v229
	v_cvt_pk_f32_fp8_sdwa v[48:49], v229 src0_sel:WORD_1
	v_pk_fma_f32 v[30:31], v[46:47], v[20:21], v[30:31] op_sel_hi:[1,0,1]
	v_pk_fma_f32 v[32:33], v[48:49], v[20:21], v[32:33] op_sel_hi:[1,0,1]
	v_cvt_pk_f32_fp8_e32 v[42:43], v230
	v_cvt_pk_f32_fp8_sdwa v[44:45], v230 src0_sel:WORD_1
	v_pk_fma_f32 v[34:35], v[42:43], v[20:21], v[34:35] op_sel_hi:[1,0,1]
	v_pk_fma_f32 v[36:37], v[44:45], v[20:21], v[36:37] op_sel_hi:[1,0,1]
	v_cvt_pk_f32_fp8_e32 v[46:47], v231
	v_cvt_pk_f32_fp8_sdwa v[48:49], v231 src0_sel:WORD_1
	v_pk_fma_f32 v[38:39], v[46:47], v[20:21], v[38:39] op_sel_hi:[1,0,1]
	v_pk_fma_f32 v[40:41], v[48:49], v[20:21], v[40:41] op_sel_hi:[1,0,1]
	v_cvt_pk_f32_fp8_e32 v[42:43], v232
	v_cvt_pk_f32_fp8_sdwa v[44:45], v232 src0_sel:WORD_1
	v_pk_fma_f32 v[26:27], v[42:43], v[20:21], v[26:27] op_sel:[0,1,0] op_sel_hi:[1,1,1]
	v_pk_fma_f32 v[28:29], v[44:45], v[20:21], v[28:29] op_sel:[0,1,0] op_sel_hi:[1,1,1]
	v_cvt_pk_f32_fp8_e32 v[46:47], v233
	v_cvt_pk_f32_fp8_sdwa v[48:49], v233 src0_sel:WORD_1
	v_pk_fma_f32 v[30:31], v[46:47], v[20:21], v[30:31] op_sel:[0,1,0] op_sel_hi:[1,1,1]
	v_pk_fma_f32 v[32:33], v[48:49], v[20:21], v[32:33] op_sel:[0,1,0] op_sel_hi:[1,1,1]
; __device__ __forceinline__ float wsum(float v) { v = dpp_row_sum16(v); v += __shfl_xor(v, 16); v += __shfl_xor(v, 32); return v; }
; __device__ __forceinline__ void phase5(const Params& p, char* smem, const bool store_x = true) {
;     ...
;     float x2[16];
; #pragma unroll
;     for (int i = 0; i < 4; i++) {
;       const float4 xv = i == 0 ? xv0 : i == 1 ? xv1 : i == 2 ? xv2 : xv3;
;       x2[4 * i] = xv.x + o2[2 * i].x; x2[4 * i + 1] = xv.y + o2[2 * i].y; x2[4 * i + 2] = xv.z + o2[2 * i + 1].x; x2[4 * i + 3] = xv.w + o2[2 * i + 1].y;
;     }
;     float ss = 0.f;
; #pragma unroll
;     for (int i = 0; i < 16; i++) ss += x2[i] * x2[i];
;     ss = wsum(ss);
;     const float rs = rsqrtf(ss * (1.f / 1024.f) + EPSF);
;     if (store_x) {
; #pragma unroll
;       for (int i = 0; i < 4; i++) *(float4*)(xr + i * 4) = make_float4(x2[4 * i], x2[4 * i + 1], x2[4 * i + 2], x2[4 * i + 3]);
;     }
	v_cvt_pk_f32_fp8_e32 v[42:43], v234
	v_cvt_pk_f32_fp8_sdwa v[44:45], v234 src0_sel:WORD_1
	v_pk_fma_f32 v[34:35], v[42:43], v[20:21], v[34:35] op_sel:[0,1,0] op_sel_hi:[1,1,1]
	v_pk_fma_f32 v[36:37], v[44:45], v[20:21], v[36:37] op_sel:[0,1,0] op_sel_hi:[1,1,1]
	v_cvt_pk_f32_fp8_e32 v[46:47], v235
	v_cvt_pk_f32_fp8_sdwa v[48:49], v235 src0_sel:WORD_1
	v_pk_fma_f32 v[38:39], v[46:47], v[20:21], v[38:39] op_sel:[0,1,0] op_sel_hi:[1,1,1]
	v_pk_fma_f32 v[40:41], v[48:49], v[20:21], v[40:41] op_sel:[0,1,0] op_sel_hi:[1,1,1]
	v_cvt_pk_f32_fp8_e32 v[42:43], v236
	v_cvt_pk_f32_fp8_sdwa v[44:45], v236 src0_sel:WORD_1
	v_pk_fma_f32 v[26:27], v[42:43], v[22:23], v[26:27] op_sel_hi:[1,0,1]
	v_pk_fma_f32 v[28:29], v[44:45], v[22:23], v[28:29] op_sel_hi:[1,0,1]
	v_cvt_pk_f32_fp8_e32 v[46:47], v237
	v_cvt_pk_f32_fp8_sdwa v[48:49], v237 src0_sel:WORD_1
	v_pk_fma_f32 v[30:31], v[46:47], v[22:23], v[30:31] op_sel_hi:[1,0,1]
	v_pk_fma_f32 v[32:33], v[48:49], v[22:23], v[32:33] op_sel_hi:[1,0,1]
	v_cvt_pk_f32_fp8_e32 v[42:43], v238
	v_cvt_pk_f32_fp8_sdwa v[44:45], v238 src0_sel:WORD_1
	v_pk_fma_f32 v[34:35], v[42:43], v[22:23], v[34:35] op_sel_hi:[1,0,1]
	v_pk_fma_f32 v[36:37], v[44:45], v[22:23], v[36:37] op_sel_hi:[1,0,1]
	v_cvt_pk_f32_fp8_e32 v[46:47], v239
	v_cvt_pk_f32_fp8_sdwa v[48:49], v239 src0_sel:WORD_1
	v_pk_fma_f32 v[38:39], v[46:47], v[22:23], v[38:39] op_sel_hi:[1,0,1]
	v_pk_fma_f32 v[40:41], v[48:49], v[22:23], v[40:41] op_sel_hi:[1,0,1]
	v_cvt_pk_f32_fp8_e32 v[42:43], v240
	v_cvt_pk_f32_fp8_sdwa v[44:45], v240 src0_sel:WORD_1
	v_pk_fma_f32 v[26:27], v[42:43], v[22:23], v[26:27] op_sel:[0,1,0] op_sel_hi:[1,1,1]
	v_pk_fma_f32 v[28:29], v[44:45], v[22:23], v[28:29] op_sel:[0,1,0] op_sel_hi:[1,1,1]
	v_cvt_pk_f32_fp8_e32 v[46:47], v241
	v_cvt_pk_f32_fp8_sdwa v[48:49], v241 src0_sel:WORD_1
	v_pk_fma_f32 v[30:31], v[46:47], v[22:23], v[30:31] op_sel:[0,1,0] op_sel_hi:[1,1,1]
	v_pk_fma_f32 v[32:33], v[48:49], v[22:23], v[32:33] op_sel:[0,1,0] op_sel_hi:[1,1,1]
	v_cvt_pk_f32_fp8_e32 v[42:43], v242
	v_cvt_pk_f32_fp8_sdwa v[44:45], v242 src0_sel:WORD_1
	v_pk_fma_f32 v[34:35], v[42:43], v[22:23], v[34:35] op_sel:[0,1,0] op_sel_hi:[1,1,1]
	v_pk_fma_f32 v[36:37], v[44:45], v[22:23], v[36:37] op_sel:[0,1,0] op_sel_hi:[1,1,1]
	v_cvt_pk_f32_fp8_e32 v[46:47], v243
	v_cvt_pk_f32_fp8_sdwa v[48:49], v243 src0_sel:WORD_1
	v_pk_fma_f32 v[38:39], v[46:47], v[22:23], v[38:39] op_sel:[0,1,0] op_sel_hi:[1,1,1]
	v_pk_fma_f32 v[40:41], v[48:49], v[22:23], v[40:41] op_sel:[0,1,0] op_sel_hi:[1,1,1]
	v_cvt_pk_f32_fp8_e32 v[42:43], v244
	v_cvt_pk_f32_fp8_sdwa v[44:45], v244 src0_sel:WORD_1
	v_pk_fma_f32 v[26:27], v[42:43], v[24:25], v[26:27] op_sel_hi:[1,0,1]
	v_pk_fma_f32 v[28:29], v[44:45], v[24:25], v[28:29] op_sel_hi:[1,0,1]
	v_cvt_pk_f32_fp8_e32 v[46:47], v245
	v_cvt_pk_f32_fp8_sdwa v[48:49], v245 src0_sel:WORD_1
	v_pk_fma_f32 v[30:31], v[46:47], v[24:25], v[30:31] op_sel_hi:[1,0,1]
	v_pk_fma_f32 v[32:33], v[48:49], v[24:25], v[32:33] op_sel_hi:[1,0,1]
	v_cvt_pk_f32_fp8_e32 v[42:43], v246
	v_cvt_pk_f32_fp8_sdwa v[44:45], v246 src0_sel:WORD_1
	v_pk_fma_f32 v[34:35], v[42:43], v[24:25], v[34:35] op_sel_hi:[1,0,1]
	v_pk_fma_f32 v[36:37], v[44:45], v[24:25], v[36:37] op_sel_hi:[1,0,1]
	v_cvt_pk_f32_fp8_e32 v[46:47], v247
	v_cvt_pk_f32_fp8_sdwa v[48:49], v247 src0_sel:WORD_1
	v_pk_fma_f32 v[38:39], v[46:47], v[24:25], v[38:39] op_sel_hi:[1,0,1]
	v_pk_fma_f32 v[40:41], v[48:49], v[24:25], v[40:41] op_sel_hi:[1,0,1]
	v_cvt_pk_f32_fp8_e32 v[42:43], v248
	v_cvt_pk_f32_fp8_sdwa v[44:45], v248 src0_sel:WORD_1
	v_pk_fma_f32 v[26:27], v[42:43], v[24:25], v[26:27] op_sel:[0,1,0] op_sel_hi:[1,1,1]
	v_pk_fma_f32 v[28:29], v[44:45], v[24:25], v[28:29] op_sel:[0,1,0] op_sel_hi:[1,1,1]
	v_cvt_pk_f32_fp8_e32 v[46:47], v249
	v_cvt_pk_f32_fp8_sdwa v[48:49], v249 src0_sel:WORD_1
	v_pk_fma_f32 v[30:31], v[46:47], v[24:25], v[30:31] op_sel:[0,1,0] op_sel_hi:[1,1,1]
	v_pk_fma_f32 v[32:33], v[48:49], v[24:25], v[32:33] op_sel:[0,1,0] op_sel_hi:[1,1,1]
	v_cvt_pk_f32_fp8_e32 v[42:43], v250
	v_cvt_pk_f32_fp8_sdwa v[44:45], v250 src0_sel:WORD_1
	v_pk_fma_f32 v[34:35], v[42:43], v[24:25], v[34:35] op_sel:[0,1,0] op_sel_hi:[1,1,1]
	v_pk_fma_f32 v[36:37], v[44:45], v[24:25], v[36:37] op_sel:[0,1,0] op_sel_hi:[1,1,1]
	v_cvt_pk_f32_fp8_e32 v[46:47], v251
	v_cvt_pk_f32_fp8_sdwa v[48:49], v251 src0_sel:WORD_1
	v_pk_fma_f32 v[38:39], v[46:47], v[24:25], v[38:39] op_sel:[0,1,0] op_sel_hi:[1,1,1]
	v_pk_fma_f32 v[40:41], v[48:49], v[24:25], v[40:41] op_sel:[0,1,0] op_sel_hi:[1,1,1]
	s_nop 1
	v_permlane32_swap_b32_e32 v26, v34
	v_permlane32_swap_b32_e32 v27, v35
	v_permlane32_swap_b32_e32 v28, v36
	v_permlane32_swap_b32_e32 v29, v37
	v_permlane32_swap_b32_e32 v30, v38
	v_permlane32_swap_b32_e32 v31, v39
	v_permlane32_swap_b32_e32 v32, v40
	v_permlane32_swap_b32_e32 v33, v41
	v_add_f32_e32 v26, v26, v34
	v_add_f32_e32 v27, v27, v35
	v_add_f32_e32 v28, v28, v36
	v_add_f32_e32 v29, v29, v37
	v_add_f32_e32 v30, v30, v38
	v_add_f32_e32 v31, v31, v39
	v_add_f32_e32 v32, v32, v40
	v_add_f32_e32 v33, v33, v41
	s_nop 1
	v_permlane16_swap_b32_e32 v26, v30
	v_permlane16_swap_b32_e32 v27, v31
	v_permlane16_swap_b32_e32 v28, v32
	v_permlane16_swap_b32_e32 v29, v33
	v_add_f32_e32 v26, v26, v30
	v_add_f32_e32 v27, v27, v31
	v_add_f32_e32 v28, v28, v32
	v_add_f32_e32 v29, v29, v33
	s_lshl_b32 s11, s12, 12
	v_add_u32_e32 v6, s11, v3
	v_add_f32_dpp v42, v26, v26 row_ror:8 row_mask:0xf bank_mask:0xf
	v_add_f32_dpp v43, v28, v28 row_ror:8 row_mask:0xf bank_mask:0xf
	v_add_f32_dpp v44, v27, v27 row_ror:8 row_mask:0xf bank_mask:0xf
	v_add_f32_dpp v45, v29, v29 row_ror:8 row_mask:0xf bank_mask:0xf
	v_cndmask_b32_e64 v46, v42, v43, s[14:15]
	v_cndmask_b32_e64 v47, v44, v45, s[14:15]
	v_add_f32_e32 v46, v54, v46
	v_add_f32_e32 v47, v55, v47
	global_store_dwordx2 v6, v[46:47], s[6:7]
	v_mul_f32_e32 v48, v46, v46
	v_fmac_f32_e32 v48, v47, v47
	s_lshl_b32 s11, s12, 2
	s_add_u32 s11, s11, 0x1100000
	v_mov_b32_e32 v7, s11
	v_add_f32_dpp v48, v48, v48 quad_perm:[1,0,3,2] row_mask:0xf bank_mask:0xf
	s_nop 1
	v_add_f32_dpp v48, v48, v48 quad_perm:[2,3,0,1] row_mask:0xf bank_mask:0xf
	s_nop 1
	v_add_f32_dpp v48, v48, v48 row_half_mirror row_mask:0xf bank_mask:0xf
	s_nop 1
	v_add_f32_dpp v48, v48, v48 row_mirror row_mask:0xf bank_mask:0xf
	s_nop 1
	v_add_f32_dpp v48, v48, v48 row_bcast:15 row_mask:0xa bank_mask:0xf
	s_nop 1
	v_add_f32_dpp v48, v48, v48 row_bcast:31 row_mask:0xc bank_mask:0xf
	s_nop 1
	s_mov_b32 exec_lo, 0
	s_brev_b32 exec_hi, 1
	global_atomic_add_f32 v7, v48, s[4:5]
	s_mov_b64 exec, -1
; #define P5_LOAD(A, TAB, j0)                                                                \
;   _Pragma("unroll") for (int q = 0; q < 16; q++) {                                         \
;     A[q] = ((const uint4*)((TAB) + (size_t)widx[(j0) + q] * 1024))[lane];                  \
;   }
; __device__ __forceinline__ void phase5(const Params& p, char* smem, const bool store_x = true) {
;     ...
; #pragma unroll 1
;     for (int j0 = 0; j0 < 128; j0 += 32) {
;       P5_LOAD(A1, EV, j0 + 16)
;       P5_COMPUTE_V(A0, j0)
;       if (j0 + 32 < 128) { P5_LOAD(A0, EV, j0 + 32) }
;       P5_COMPUTE_V(A1, j0 + 16)
;     }
.Lp5v_skip2:
	s_add_u32 s10, s8, s33
	s_min_u32 s10, s10, s13
	s_lshl_b32 s18, s10, 10
	s_add_u32 s11, s16, 11
	s_and_b32 s11, s11, 15
	s_lshl_b32 s11, s11, 10
	s_add_u32 s11, s11, s17
	s_mov_b32 m0, s11
	v_lshl_add_u64 v[4:5], v[58:59], 0, s[18:19]
	global_load_lds_dwordx4 v[4:5], off
	s_add_u32 s11, s16, 6
	s_and_b32 s11, s11, 15
	s_lshl_b32 s11, s11, 10
	v_add_u32_e32 v8, s11, v2
	ds_read_b128 v[10:13], v8 offset:0
	ds_read_b128 v[14:17], v8 offset:16
	ds_read_b128 v[18:21], v8 offset:32
	ds_read_b128 v[22:25], v8 offset:48
	s_add_u32 s10, s8, s25
	s_min_u32 s10, s10, s13
	s_lshl_b32 s11, s10, 12
	v_add_u32_e32 v6, s11, v3
	global_load_dwordx2 v[54:55], v6, s[6:7]
	s_waitcnt lgkmcnt(0)
	v_add_u32_e32 v10, v10, v1
	global_load_dwordx4 v[188:191], v10, s[2:3]
	v_add_u32_e32 v11, v11, v1
	global_load_dwordx4 v[192:195], v11, s[2:3]
	v_add_u32_e32 v12, v12, v1
	global_load_dwordx4 v[196:199], v12, s[2:3]
	v_add_u32_e32 v13, v13, v1
	global_load_dwordx4 v[200:203], v13, s[2:3]
	v_add_u32_e32 v14, v14, v1
	global_load_dwordx4 v[204:207], v14, s[2:3]
	v_add_u32_e32 v15, v15, v1
	global_load_dwordx4 v[208:211], v15, s[2:3]
	v_add_u32_e32 v16, v16, v1
	global_load_dwordx4 v[212:215], v16, s[2:3]
	v_add_u32_e32 v17, v17, v1
	global_load_dwordx4 v[216:219], v17, s[2:3]
	v_add_u32_e32 v18, v18, v1
	global_load_dwordx4 v[220:223], v18, s[2:3]
	v_add_u32_e32 v19, v19, v1
	global_load_dwordx4 v[224:227], v19, s[2:3]
	v_add_u32_e32 v20, v20, v1
	global_load_dwordx4 v[228:231], v20, s[2:3]
	v_add_u32_e32 v21, v21, v1
	global_load_dwordx4 v[232:235], v21, s[2:3]
	v_add_u32_e32 v22, v22, v1
	global_load_dwordx4 v[236:239], v22, s[2:3]
	v_add_u32_e32 v23, v23, v1
	global_load_dwordx4 v[240:243], v23, s[2:3]
	v_add_u32_e32 v24, v24, v1
	global_load_dwordx4 v[244:247], v24, s[2:3]
	v_add_u32_e32 v25, v25, v1
	global_load_dwordx4 v[248:251], v25, s[2:3]
	s_add_u32 s11, s16, 3
	s_and_b32 s11, s11, 15
	s_lshl_b32 s11, s11, 10
	v_add_u32_e32 v8, s11, v2
	ds_read_b128 v[10:13], v8 offset:512
	ds_read_b128 v[14:17], v8 offset:528
	ds_read_b128 v[18:21], v8 offset:544
	ds_read_b128 v[22:25], v8 offset:560
	s_add_u32 s12, s8, s22
	s_waitcnt vmcnt(60) lgkmcnt(0)
	s_cmp_lt_u32 s12, 0x4200
	s_cbranch_scc0 .Lp5v_skip3
	v_accvgpr_read_b32 v8, a0
	v_cvt_pk_f32_fp8_e32 v[42:43], v8
	v_cvt_pk_f32_fp8_sdwa v[44:45], v8 src0_sel:WORD_1
	v_pk_mul_f32 v[26:27], v[42:43], v[10:11] op_sel_hi:[1,0]
	v_pk_mul_f32 v[28:29], v[44:45], v[10:11] op_sel_hi:[1,0]
	v_accvgpr_read_b32 v9, a1
	v_cvt_pk_f32_fp8_e32 v[46:47], v9
	v_cvt_pk_f32_fp8_sdwa v[48:49], v9 src0_sel:WORD_1
	v_pk_mul_f32 v[30:31], v[46:47], v[10:11] op_sel_hi:[1,0]
	v_pk_mul_f32 v[32:33], v[48:49], v[10:11] op_sel_hi:[1,0]
	v_accvgpr_read_b32 v8, a2
	v_cvt_pk_f32_fp8_e32 v[42:43], v8
	v_cvt_pk_f32_fp8_sdwa v[44:45], v8 src0_sel:WORD_1
	v_pk_mul_f32 v[34:35], v[42:43], v[10:11] op_sel_hi:[1,0]
	v_pk_mul_f32 v[36:37], v[44:45], v[10:11] op_sel_hi:[1,0]
	v_accvgpr_read_b32 v9, a3
	v_cvt_pk_f32_fp8_e32 v[46:47], v9
	v_cvt_pk_f32_fp8_sdwa v[48:49], v9 src0_sel:WORD_1
	v_pk_mul_f32 v[38:39], v[46:47], v[10:11] op_sel_hi:[1,0]
	v_pk_mul_f32 v[40:41], v[48:49], v[10:11] op_sel_hi:[1,0]
	v_accvgpr_read_b32 v8, a4
	v_cvt_pk_f32_fp8_e32 v[42:43], v8
	v_cvt_pk_f32_fp8_sdwa v[44:45], v8 src0_sel:WORD_1
	v_pk_fma_f32 v[26:27], v[42:43], v[10:11], v[26:27] op_sel:[0,1,0] op_sel_hi:[1,1,1]
	v_pk_fma_f32 v[28:29], v[44:45], v[10:11], v[28:29] op_sel:[0,1,0] op_sel_hi:[1,1,1]
	v_accvgpr_read_b32 v9, a5
	v_cvt_pk_f32_fp8_e32 v[46:47], v9
	v_cvt_pk_f32_fp8_sdwa v[48:49], v9 src0_sel:WORD_1
	v_pk_fma_f32 v[30:31], v[46:47], v[10:11], v[30:31] op_sel:[0,1,0] op_sel_hi:[1,1,1]
	v_pk_fma_f32 v[32:33], v[48:49], v[10:11], v[32:33] op_sel:[0,1,0] op_sel_hi:[1,1,1]
	v_accvgpr_read_b32 v8, a6
	v_cvt_pk_f32_fp8_e32 v[42:43], v8
	v_cvt_pk_f32_fp8_sdwa v[44:45], v8 src0_sel:WORD_1
	v_pk_fma_f32 v[34:35], v[42:43], v[10:11], v[34:35] op_sel:[0,1,0] op_sel_hi:[1,1,1]
	v_pk_fma_f32 v[36:37], v[44:45], v[10:11], v[36:37] op_sel:[0,1,0] op_sel_hi:[1,1,1]
	v_accvgpr_read_b32 v9, a7
	v_cvt_pk_f32_fp8_e32 v[46:47], v9
	v_cvt_pk_f32_fp8_sdwa v[48:49], v9 src0_sel:WORD_1
	v_pk_fma_f32 v[38:39], v[46:47], v[10:11], v[38:39] op_sel:[0,1,0] op_sel_hi:[1,1,1]
	v_pk_fma_f32 v[40:41], v[48:49], v[10:11], v[40:41] op_sel:[0,1,0] op_sel_hi:[1,1,1]
	v_accvgpr_read_b32 v8, a8
	v_cvt_pk_f32_fp8_e32 v[42:43], v8
	v_cvt_pk_f32_fp8_sdwa v[44:45], v8 src0_sel:WORD_1
	v_pk_fma_f32 v[26:27], v[42:43], v[12:13], v[26:27] op_sel_hi:[1,0,1]
	v_pk_fma_f32 v[28:29], v[44:45], v[12:13], v[28:29] op_sel_hi:[1,0,1]
	v_accvgpr_read_b32 v9, a9
	v_cvt_pk_f32_fp8_e32 v[46:47], v9
	v_cvt_pk_f32_fp8_sdwa v[48:49], v9 src0_sel:WORD_1
	v_pk_fma_f32 v[30:31], v[46:47], v[12:13], v[30:31] op_sel_hi:[1,0,1]
	v_pk_fma_f32 v[32:33], v[48:49], v[12:13], v[32:33] op_sel_hi:[1,0,1]
	v_accvgpr_read_b32 v8, a10
	v_cvt_pk_f32_fp8_e32 v[42:43], v8
	v_cvt_pk_f32_fp8_sdwa v[44:45], v8 src0_sel:WORD_1
	v_pk_fma_f32 v[34:35], v[42:43], v[12:13], v[34:35] op_sel_hi:[1,0,1]
	v_pk_fma_f32 v[36:37], v[44:45], v[12:13], v[36:37] op_sel_hi:[1,0,1]
	v_accvgpr_read_b32 v9, a11
	v_cvt_pk_f32_fp8_e32 v[46:47], v9
	v_cvt_pk_f32_fp8_sdwa v[48:49], v9 src0_sel:WORD_1
	v_pk_fma_f32 v[38:39], v[46:47], v[12:13], v[38:39] op_sel_hi:[1,0,1]
	v_pk_fma_f32 v[40:41], v[48:49], v[12:13], v[40:41] op_sel_hi:[1,0,1]
	v_accvgpr_read_b32 v8, a12
	v_cvt_pk_f32_fp8_e32 v[42:43], v8
	v_cvt_pk_f32_fp8_sdwa v[44:45], v8 src0_sel:WORD_1
	v_pk_fma_f32 v[26:27], v[42:43], v[12:13], v[26:27] op_sel:[0,1,0] op_sel_hi:[1,1,1]
	v_pk_fma_f32 v[28:29], v[44:45], v[12:13], v[28:29] op_sel:[0,1,0] op_sel_hi:[1,1,1]
	v_accvgpr_read_b32 v9, a13
	v_cvt_pk_f32_fp8_e32 v[46:47], v9
	v_cvt_pk_f32_fp8_sdwa v[48:49], v9 src0_sel:WORD_1
	v_pk_fma_f32 v[30:31], v[46:47], v[12:13], v[30:31] op_sel:[0,1,0] op_sel_hi:[1,1,1]
	v_pk_fma_f32 v[32:33], v[48:49], v[12:13], v[32:33] op_sel:[0,1,0] op_sel_hi:[1,1,1]
	v_accvgpr_read_b32 v8, a14
	v_cvt_pk_f32_fp8_e32 v[42:43], v8
	v_cvt_pk_f32_fp8_sdwa v[44:45], v8 src0_sel:WORD_1
	v_pk_fma_f32 v[34:35], v[42:43], v[12:13], v[34:35] op_sel:[0,1,0] op_sel_hi:[1,1,1]
	v_pk_fma_f32 v[36:37], v[44:45], v[12:13], v[36:37] op_sel:[0,1,0] op_sel_hi:[1,1,1]
	v_accvgpr_read_b32 v9, a15
	v_cvt_pk_f32_fp8_e32 v[46:47], v9
	v_cvt_pk_f32_fp8_sdwa v[48:49], v9 src0_sel:WORD_1
	v_pk_fma_f32 v[38:39], v[46:47], v[12:13], v[38:39] op_sel:[0,1,0] op_sel_hi:[1,1,1]
	v_pk_fma_f32 v[40:41], v[48:49], v[12:13], v[40:41] op_sel:[0,1,0] op_sel_hi:[1,1,1]
	v_accvgpr_read_b32 v8, a16
	v_cvt_pk_f32_fp8_e32 v[42:43], v8
	v_cvt_pk_f32_fp8_sdwa v[44:45], v8 src0_sel:WORD_1
	v_pk_fma_f32 v[26:27], v[42:43], v[14:15], v[26:27] op_sel_hi:[1,0,1]
	v_pk_fma_f32 v[28:29], v[44:45], v[14:15], v[28:29] op_sel_hi:[1,0,1]
	v_accvgpr_read_b32 v9, a17
	v_cvt_pk_f32_fp8_e32 v[46:47], v9
	v_cvt_pk_f32_fp8_sdwa v[48:49], v9 src0_sel:WORD_1
	v_pk_fma_f32 v[30:31], v[46:47], v[14:15], v[30:31] op_sel_hi:[1,0,1]
	v_pk_fma_f32 v[32:33], v[48:49], v[14:15], v[32:33] op_sel_hi:[1,0,1]
	v_accvgpr_read_b32 v8, a18
	v_cvt_pk_f32_fp8_e32 v[42:43], v8
	v_cvt_pk_f32_fp8_sdwa v[44:45], v8 src0_sel:WORD_1
	v_pk_fma_f32 v[34:35], v[42:43], v[14:15], v[34:35] op_sel_hi:[1,0,1]
	v_pk_fma_f32 v[36:37], v[44:45], v[14:15], v[36:37] op_sel_hi:[1,0,1]
	v_accvgpr_read_b32 v9, a19
	v_cvt_pk_f32_fp8_e32 v[46:47], v9
	v_cvt_pk_f32_fp8_sdwa v[48:49], v9 src0_sel:WORD_1
	v_pk_fma_f32 v[38:39], v[46:47], v[14:15], v[38:39] op_sel_hi:[1,0,1]
	v_pk_fma_f32 v[40:41], v[48:49], v[14:15], v[40:41] op_sel_hi:[1,0,1]
	v_accvgpr_read_b32 v8, a20
	v_cvt_pk_f32_fp8_e32 v[42:43], v8
	v_cvt_pk_f32_fp8_sdwa v[44:45], v8 src0_sel:WORD_1
	v_pk_fma_f32 v[26:27], v[42:43], v[14:15], v[26:27] op_sel:[0,1,0] op_sel_hi:[1,1,1]
	v_pk_fma_f32 v[28:29], v[44:45], v[14:15], v[28:29] op_sel:[0,1,0] op_sel_hi:[1,1,1]
	v_accvgpr_read_b32 v9, a21
	v_cvt_pk_f32_fp8_e32 v[46:47], v9
	v_cvt_pk_f32_fp8_sdwa v[48:49], v9 src0_sel:WORD_1
	v_pk_fma_f32 v[30:31], v[46:47], v[14:15], v[30:31] op_sel:[0,1,0] op_sel_hi:[1,1,1]
	v_pk_fma_f32 v[32:33], v[48:49], v[14:15], v[32:33] op_sel:[0,1,0] op_sel_hi:[1,1,1]
	v_accvgpr_read_b32 v8, a22
	v_cvt_pk_f32_fp8_e32 v[42:43], v8
	v_cvt_pk_f32_fp8_sdwa v[44:45], v8 src0_sel:WORD_1
	v_pk_fma_f32 v[34:35], v[42:43], v[14:15], v[34:35] op_sel:[0,1,0] op_sel_hi:[1,1,1]
	v_pk_fma_f32 v[36:37], v[44:45], v[14:15], v[36:37] op_sel:[0,1,0] op_sel_hi:[1,1,1]
	v_accvgpr_read_b32 v9, a23
	v_cvt_pk_f32_fp8_e32 v[46:47], v9
	v_cvt_pk_f32_fp8_sdwa v[48:49], v9 src0_sel:WORD_1
	v_pk_fma_f32 v[38:39], v[46:47], v[14:15], v[38:39] op_sel:[0,1,0] op_sel_hi:[1,1,1]
	v_pk_fma_f32 v[40:41], v[48:49], v[14:15], v[40:41] op_sel:[0,1,0] op_sel_hi:[1,1,1]
	v_accvgpr_read_b32 v8, a24
	v_cvt_pk_f32_fp8_e32 v[42:43], v8
	v_cvt_pk_f32_fp8_sdwa v[44:45], v8 src0_sel:WORD_1
	v_pk_fma_f32 v[26:27], v[42:43], v[16:17], v[26:27] op_sel_hi:[1,0,1]
	v_pk_fma_f32 v[28:29], v[44:45], v[16:17], v[28:29] op_sel_hi:[1,0,1]
	v_accvgpr_read_b32 v9, a25
	v_cvt_pk_f32_fp8_e32 v[46:47], v9
	v_cvt_pk_f32_fp8_sdwa v[48:49], v9 src0_sel:WORD_1
	v_pk_fma_f32 v[30:31], v[46:47], v[16:17], v[30:31] op_sel_hi:[1,0,1]
	v_pk_fma_f32 v[32:33], v[48:49], v[16:17], v[32:33] op_sel_hi:[1,0,1]
	v_accvgpr_read_b32 v8, a26
	v_cvt_pk_f32_fp8_e32 v[42:43], v8
	v_cvt_pk_f32_fp8_sdwa v[44:45], v8 src0_sel:WORD_1
	v_pk_fma_f32 v[34:35], v[42:43], v[16:17], v[34:35] op_sel_hi:[1,0,1]
	v_pk_fma_f32 v[36:37], v[44:45], v[16:17], v[36:37] op_sel_hi:[1,0,1]
	v_accvgpr_read_b32 v9, a27
	v_cvt_pk_f32_fp8_e32 v[46:47], v9
	v_cvt_pk_f32_fp8_sdwa v[48:49], v9 src0_sel:WORD_1
	v_pk_fma_f32 v[38:39], v[46:47], v[16:17], v[38:39] op_sel_hi:[1,0,1]
	v_pk_fma_f32 v[40:41], v[48:49], v[16:17], v[40:41] op_sel_hi:[1,0,1]
	v_accvgpr_read_b32 v8, a28
	v_cvt_pk_f32_fp8_e32 v[42:43], v8
	v_cvt_pk_f32_fp8_sdwa v[44:45], v8 src0_sel:WORD_1
	v_pk_fma_f32 v[26:27], v[42:43], v[16:17], v[26:27] op_sel:[0,1,0] op_sel_hi:[1,1,1]
	v_pk_fma_f32 v[28:29], v[44:45], v[16:17], v[28:29] op_sel:[0,1,0] op_sel_hi:[1,1,1]
	v_accvgpr_read_b32 v9, a29
	v_cvt_pk_f32_fp8_e32 v[46:47], v9
	v_cvt_pk_f32_fp8_sdwa v[48:49], v9 src0_sel:WORD_1
	v_pk_fma_f32 v[30:31], v[46:47], v[16:17], v[30:31] op_sel:[0,1,0] op_sel_hi:[1,1,1]
	v_pk_fma_f32 v[32:33], v[48:49], v[16:17], v[32:33] op_sel:[0,1,0] op_sel_hi:[1,1,1]
	v_accvgpr_read_b32 v8, a30
	v_cvt_pk_f32_fp8_e32 v[42:43], v8
	v_cvt_pk_f32_fp8_sdwa v[44:45], v8 src0_sel:WORD_1
	v_pk_fma_f32 v[34:35], v[42:43], v[16:17], v[34:35] op_sel:[0,1,0] op_sel_hi:[1,1,1]
	v_pk_fma_f32 v[36:37], v[44:45], v[16:17], v[36:37] op_sel:[0,1,0] op_sel_hi:[1,1,1]
	v_accvgpr_read_b32 v9, a31
	v_cvt_pk_f32_fp8_e32 v[46:47], v9
	v_cvt_pk_f32_fp8_sdwa v[48:49], v9 src0_sel:WORD_1
	v_pk_fma_f32 v[38:39], v[46:47], v[16:17], v[38:39] op_sel:[0,1,0] op_sel_hi:[1,1,1]
	v_pk_fma_f32 v[40:41], v[48:49], v[16:17], v[40:41] op_sel:[0,1,0] op_sel_hi:[1,1,1]
	v_accvgpr_read_b32 v8, a32
	v_cvt_pk_f32_fp8_e32 v[42:43], v8
	v_cvt_pk_f32_fp8_sdwa v[44:45], v8 src0_sel:WORD_1
	v_pk_fma_f32 v[26:27], v[42:43], v[18:19], v[26:27] op_sel_hi:[1,0,1]
	v_pk_fma_f32 v[28:29], v[44:45], v[18:19], v[28:29] op_sel_hi:[1,0,1]
	v_accvgpr_read_b32 v9, a33
	v_cvt_pk_f32_fp8_e32 v[46:47], v9
	v_cvt_pk_f32_fp8_sdwa v[48:49], v9 src0_sel:WORD_1
	v_pk_fma_f32 v[30:31], v[46:47], v[18:19], v[30:31] op_sel_hi:[1,0,1]
	v_pk_fma_f32 v[32:33], v[48:49], v[18:19], v[32:33] op_sel_hi:[1,0,1]
	v_accvgpr_read_b32 v8, a34
	v_cvt_pk_f32_fp8_e32 v[42:43], v8
	v_cvt_pk_f32_fp8_sdwa v[44:45], v8 src0_sel:WORD_1
	v_pk_fma_f32 v[34:35], v[42:43], v[18:19], v[34:35] op_sel_hi:[1,0,1]
	v_pk_fma_f32 v[36:37], v[44:45], v[18:19], v[36:37] op_sel_hi:[1,0,1]
	v_accvgpr_read_b32 v9, a35
	v_cvt_pk_f32_fp8_e32 v[46:47], v9
	v_cvt_pk_f32_fp8_sdwa v[48:49], v9 src0_sel:WORD_1
	v_pk_fma_f32 v[38:39], v[46:47], v[18:19], v[38:39] op_sel_hi:[1,0,1]
	v_pk_fma_f32 v[40:41], v[48:49], v[18:19], v[40:41] op_sel_hi:[1,0,1]
	v_accvgpr_read_b32 v8, a36
	v_cvt_pk_f32_fp8_e32 v[42:43], v8
	v_cvt_pk_f32_fp8_sdwa v[44:45], v8 src0_sel:WORD_1
	v_pk_fma_f32 v[26:27], v[42:43], v[18:19], v[26:27] op_sel:[0,1,0] op_sel_hi:[1,1,1]
	v_pk_fma_f32 v[28:29], v[44:45], v[18:19], v[28:29] op_sel:[0,1,0] op_sel_hi:[1,1,1]
	v_accvgpr_read_b32 v9, a37
	v_cvt_pk_f32_fp8_e32 v[46:47], v9
	v_cvt_pk_f32_fp8_sdwa v[48:49], v9 src0_sel:WORD_1
	v_pk_fma_f32 v[30:31], v[46:47], v[18:19], v[30:31] op_sel:[0,1,0] op_sel_hi:[1,1,1]
	v_pk_fma_f32 v[32:33], v[48:49], v[18:19], v[32:33] op_sel:[0,1,0] op_sel_hi:[1,1,1]
	v_accvgpr_read_b32 v8, a38
	v_cvt_pk_f32_fp8_e32 v[42:43], v8
	v_cvt_pk_f32_fp8_sdwa v[44:45], v8 src0_sel:WORD_1
	v_pk_fma_f32 v[34:35], v[42:43], v[18:19], v[34:35] op_sel:[0,1,0] op_sel_hi:[1,1,1]
	v_pk_fma_f32 v[36:37], v[44:45], v[18:19], v[36:37] op_sel:[0,1,0] op_sel_hi:[1,1,1]
	v_accvgpr_read_b32 v9, a39
	v_cvt_pk_f32_fp8_e32 v[46:47], v9
	v_cvt_pk_f32_fp8_sdwa v[48:49], v9 src0_sel:WORD_1
	v_pk_fma_f32 v[38:39], v[46:47], v[18:19], v[38:39] op_sel:[0,1,0] op_sel_hi:[1,1,1]
	v_pk_fma_f32 v[40:41], v[48:49], v[18:19], v[40:41] op_sel:[0,1,0] op_sel_hi:[1,1,1]
	v_accvgpr_read_b32 v8, a40
	v_cvt_pk_f32_fp8_e32 v[42:43], v8
	v_cvt_pk_f32_fp8_sdwa v[44:45], v8 src0_sel:WORD_1
	v_pk_fma_f32 v[26:27], v[42:43], v[20:21], v[26:27] op_sel_hi:[1,0,1]
	v_pk_fma_f32 v[28:29], v[44:45], v[20:21], v[28:29] op_sel_hi:[1,0,1]
	v_accvgpr_read_b32 v9, a41
	v_cvt_pk_f32_fp8_e32 v[46:47], v9
	v_cvt_pk_f32_fp8_sdwa v[48:49], v9 src0_sel:WORD_1
	v_pk_fma_f32 v[30:31], v[46:47], v[20:21], v[30:31] op_sel_hi:[1,0,1]
	v_pk_fma_f32 v[32:33], v[48:49], v[20:21], v[32:33] op_sel_hi:[1,0,1]
	v_accvgpr_read_b32 v8, a42
	v_cvt_pk_f32_fp8_e32 v[42:43], v8
	v_cvt_pk_f32_fp8_sdwa v[44:45], v8 src0_sel:WORD_1
	v_pk_fma_f32 v[34:35], v[42:43], v[20:21], v[34:35] op_sel_hi:[1,0,1]
	v_pk_fma_f32 v[36:37], v[44:45], v[20:21], v[36:37] op_sel_hi:[1,0,1]
	v_accvgpr_read_b32 v9, a43
	v_cvt_pk_f32_fp8_e32 v[46:47], v9
	v_cvt_pk_f32_fp8_sdwa v[48:49], v9 src0_sel:WORD_1
	v_pk_fma_f32 v[38:39], v[46:47], v[20:21], v[38:39] op_sel_hi:[1,0,1]
	v_pk_fma_f32 v[40:41], v[48:49], v[20:21], v[40:41] op_sel_hi:[1,0,1]
	v_accvgpr_read_b32 v8, a44
	v_cvt_pk_f32_fp8_e32 v[42:43], v8
	v_cvt_pk_f32_fp8_sdwa v[44:45], v8 src0_sel:WORD_1
	v_pk_fma_f32 v[26:27], v[42:43], v[20:21], v[26:27] op_sel:[0,1,0] op_sel_hi:[1,1,1]
	v_pk_fma_f32 v[28:29], v[44:45], v[20:21], v[28:29] op_sel:[0,1,0] op_sel_hi:[1,1,1]
	v_accvgpr_read_b32 v9, a45
	v_cvt_pk_f32_fp8_e32 v[46:47], v9
	v_cvt_pk_f32_fp8_sdwa v[48:49], v9 src0_sel:WORD_1
	v_pk_fma_f32 v[30:31], v[46:47], v[20:21], v[30:31] op_sel:[0,1,0] op_sel_hi:[1,1,1]
	v_pk_fma_f32 v[32:33], v[48:49], v[20:21], v[32:33] op_sel:[0,1,0] op_sel_hi:[1,1,1]
	v_accvgpr_read_b32 v8, a46
	v_cvt_pk_f32_fp8_e32 v[42:43], v8
	v_cvt_pk_f32_fp8_sdwa v[44:45], v8 src0_sel:WORD_1
	v_pk_fma_f32 v[34:35], v[42:43], v[20:21], v[34:35] op_sel:[0,1,0] op_sel_hi:[1,1,1]
	v_pk_fma_f32 v[36:37], v[44:45], v[20:21], v[36:37] op_sel:[0,1,0] op_sel_hi:[1,1,1]
	v_accvgpr_read_b32 v9, a47
	v_cvt_pk_f32_fp8_e32 v[46:47], v9
	v_cvt_pk_f32_fp8_sdwa v[48:49], v9 src0_sel:WORD_1
	v_pk_fma_f32 v[38:39], v[46:47], v[20:21], v[38:39] op_sel:[0,1,0] op_sel_hi:[1,1,1]
	v_pk_fma_f32 v[40:41], v[48:49], v[20:21], v[40:41] op_sel:[0,1,0] op_sel_hi:[1,1,1]
	v_accvgpr_read_b32 v8, a48
	v_cvt_pk_f32_fp8_e32 v[42:43], v8
	v_cvt_pk_f32_fp8_sdwa v[44:45], v8 src0_sel:WORD_1
	v_pk_fma_f32 v[26:27], v[42:43], v[22:23], v[26:27] op_sel_hi:[1,0,1]
	v_pk_fma_f32 v[28:29], v[44:45], v[22:23], v[28:29] op_sel_hi:[1,0,1]
	v_accvgpr_read_b32 v9, a49
	v_cvt_pk_f32_fp8_e32 v[46:47], v9
	v_cvt_pk_f32_fp8_sdwa v[48:49], v9 src0_sel:WORD_1
	v_pk_fma_f32 v[30:31], v[46:47], v[22:23], v[30:31] op_sel_hi:[1,0,1]
	v_pk_fma_f32 v[32:33], v[48:49], v[22:23], v[32:33] op_sel_hi:[1,0,1]
	v_accvgpr_read_b32 v8, a50
	v_cvt_pk_f32_fp8_e32 v[42:43], v8
	v_cvt_pk_f32_fp8_sdwa v[44:45], v8 src0_sel:WORD_1
	v_pk_fma_f32 v[34:35], v[42:43], v[22:23], v[34:35] op_sel_hi:[1,0,1]
	v_pk_fma_f32 v[36:37], v[44:45], v[22:23], v[36:37] op_sel_hi:[1,0,1]
	v_accvgpr_read_b32 v9, a51
	v_cvt_pk_f32_fp8_e32 v[46:47], v9
	v_cvt_pk_f32_fp8_sdwa v[48:49], v9 src0_sel:WORD_1
	v_pk_fma_f32 v[38:39], v[46:47], v[22:23], v[38:39] op_sel_hi:[1,0,1]
	v_pk_fma_f32 v[40:41], v[48:49], v[22:23], v[40:41] op_sel_hi:[1,0,1]
	v_accvgpr_read_b32 v8, a52
	v_cvt_pk_f32_fp8_e32 v[42:43], v8
	v_cvt_pk_f32_fp8_sdwa v[44:45], v8 src0_sel:WORD_1
	v_pk_fma_f32 v[26:27], v[42:43], v[22:23], v[26:27] op_sel:[0,1,0] op_sel_hi:[1,1,1]
	v_pk_fma_f32 v[28:29], v[44:45], v[22:23], v[28:29] op_sel:[0,1,0] op_sel_hi:[1,1,1]
; __device__ __forceinline__ float wsum(float v) { v = dpp_row_sum16(v); v += __shfl_xor(v, 16); v += __shfl_xor(v, 32); return v; }
; __device__ __forceinline__ void phase5(const Params& p, char* smem, const bool store_x = true) {
;     ...
;     float x2[16];
; #pragma unroll
;     for (int i = 0; i < 4; i++) {
;       const float4 xv = i == 0 ? xv0 : i == 1 ? xv1 : i == 2 ? xv2 : xv3;
;       x2[4 * i] = xv.x + o2[2 * i].x; x2[4 * i + 1] = xv.y + o2[2 * i].y; x2[4 * i + 2] = xv.z + o2[2 * i + 1].x; x2[4 * i + 3] = xv.w + o2[2 * i + 1].y;
;     }
;     float ss = 0.f;
; #pragma unroll
;     for (int i = 0; i < 16; i++) ss += x2[i] * x2[i];
;     ss = wsum(ss);
;     const float rs = rsqrtf(ss * (1.f / 1024.f) + EPSF);
;     if (store_x) {
; #pragma unroll
;       for (int i = 0; i < 4; i++) *(float4*)(xr + i * 4) = make_float4(x2[4 * i], x2[4 * i + 1], x2[4 * i + 2], x2[4 * i + 3]);
;     }
	v_accvgpr_read_b32 v9, a53
	v_cvt_pk_f32_fp8_e32 v[46:47], v9
	v_cvt_pk_f32_fp8_sdwa v[48:49], v9 src0_sel:WORD_1
	v_pk_fma_f32 v[30:31], v[46:47], v[22:23], v[30:31] op_sel:[0,1,0] op_sel_hi:[1,1,1]
	v_pk_fma_f32 v[32:33], v[48:49], v[22:23], v[32:33] op_sel:[0,1,0] op_sel_hi:[1,1,1]
	v_accvgpr_read_b32 v8, a54
	v_cvt_pk_f32_fp8_e32 v[42:43], v8
	v_cvt_pk_f32_fp8_sdwa v[44:45], v8 src0_sel:WORD_1
	v_pk_fma_f32 v[34:35], v[42:43], v[22:23], v[34:35] op_sel:[0,1,0] op_sel_hi:[1,1,1]
	v_pk_fma_f32 v[36:37], v[44:45], v[22:23], v[36:37] op_sel:[0,1,0] op_sel_hi:[1,1,1]
	v_accvgpr_read_b32 v9, a55
	v_cvt_pk_f32_fp8_e32 v[46:47], v9
	v_cvt_pk_f32_fp8_sdwa v[48:49], v9 src0_sel:WORD_1
	v_pk_fma_f32 v[38:39], v[46:47], v[22:23], v[38:39] op_sel:[0,1,0] op_sel_hi:[1,1,1]
	v_pk_fma_f32 v[40:41], v[48:49], v[22:23], v[40:41] op_sel:[0,1,0] op_sel_hi:[1,1,1]
	v_accvgpr_read_b32 v8, a56
	v_cvt_pk_f32_fp8_e32 v[42:43], v8
	v_cvt_pk_f32_fp8_sdwa v[44:45], v8 src0_sel:WORD_1
	v_pk_fma_f32 v[26:27], v[42:43], v[24:25], v[26:27] op_sel_hi:[1,0,1]
	v_pk_fma_f32 v[28:29], v[44:45], v[24:25], v[28:29] op_sel_hi:[1,0,1]
	v_accvgpr_read_b32 v9, a57
	v_cvt_pk_f32_fp8_e32 v[46:47], v9
	v_cvt_pk_f32_fp8_sdwa v[48:49], v9 src0_sel:WORD_1
	v_pk_fma_f32 v[30:31], v[46:47], v[24:25], v[30:31] op_sel_hi:[1,0,1]
	v_pk_fma_f32 v[32:33], v[48:49], v[24:25], v[32:33] op_sel_hi:[1,0,1]
	v_accvgpr_read_b32 v8, a58
	v_cvt_pk_f32_fp8_e32 v[42:43], v8
	v_cvt_pk_f32_fp8_sdwa v[44:45], v8 src0_sel:WORD_1
	v_pk_fma_f32 v[34:35], v[42:43], v[24:25], v[34:35] op_sel_hi:[1,0,1]
	v_pk_fma_f32 v[36:37], v[44:45], v[24:25], v[36:37] op_sel_hi:[1,0,1]
	v_accvgpr_read_b32 v9, a59
	v_cvt_pk_f32_fp8_e32 v[46:47], v9
	v_cvt_pk_f32_fp8_sdwa v[48:49], v9 src0_sel:WORD_1
	v_pk_fma_f32 v[38:39], v[46:47], v[24:25], v[38:39] op_sel_hi:[1,0,1]
	v_pk_fma_f32 v[40:41], v[48:49], v[24:25], v[40:41] op_sel_hi:[1,0,1]
	v_accvgpr_read_b32 v8, a60
	v_cvt_pk_f32_fp8_e32 v[42:43], v8
	v_cvt_pk_f32_fp8_sdwa v[44:45], v8 src0_sel:WORD_1
	v_pk_fma_f32 v[26:27], v[42:43], v[24:25], v[26:27] op_sel:[0,1,0] op_sel_hi:[1,1,1]
	v_pk_fma_f32 v[28:29], v[44:45], v[24:25], v[28:29] op_sel:[0,1,0] op_sel_hi:[1,1,1]
	v_accvgpr_read_b32 v9, a61
	v_cvt_pk_f32_fp8_e32 v[46:47], v9
	v_cvt_pk_f32_fp8_sdwa v[48:49], v9 src0_sel:WORD_1
	v_pk_fma_f32 v[30:31], v[46:47], v[24:25], v[30:31] op_sel:[0,1,0] op_sel_hi:[1,1,1]
	v_pk_fma_f32 v[32:33], v[48:49], v[24:25], v[32:33] op_sel:[0,1,0] op_sel_hi:[1,1,1]
	v_accvgpr_read_b32 v8, a62
	v_cvt_pk_f32_fp8_e32 v[42:43], v8
	v_cvt_pk_f32_fp8_sdwa v[44:45], v8 src0_sel:WORD_1
	v_pk_fma_f32 v[34:35], v[42:43], v[24:25], v[34:35] op_sel:[0,1,0] op_sel_hi:[1,1,1]
	v_pk_fma_f32 v[36:37], v[44:45], v[24:25], v[36:37] op_sel:[0,1,0] op_sel_hi:[1,1,1]
	v_accvgpr_read_b32 v9, a63
	v_cvt_pk_f32_fp8_e32 v[46:47], v9
	v_cvt_pk_f32_fp8_sdwa v[48:49], v9 src0_sel:WORD_1
	v_pk_fma_f32 v[38:39], v[46:47], v[24:25], v[38:39] op_sel:[0,1,0] op_sel_hi:[1,1,1]
	v_pk_fma_f32 v[40:41], v[48:49], v[24:25], v[40:41] op_sel:[0,1,0] op_sel_hi:[1,1,1]
	s_nop 1
	v_permlane32_swap_b32_e32 v26, v34
	v_permlane32_swap_b32_e32 v27, v35
	v_permlane32_swap_b32_e32 v28, v36
	v_permlane32_swap_b32_e32 v29, v37
	v_permlane32_swap_b32_e32 v30, v38
	v_permlane32_swap_b32_e32 v31, v39
	v_permlane32_swap_b32_e32 v32, v40
	v_permlane32_swap_b32_e32 v33, v41
	v_add_f32_e32 v26, v26, v34
	v_add_f32_e32 v27, v27, v35
	v_add_f32_e32 v28, v28, v36
	v_add_f32_e32 v29, v29, v37
	v_add_f32_e32 v30, v30, v38
	v_add_f32_e32 v31, v31, v39
	v_add_f32_e32 v32, v32, v40
	v_add_f32_e32 v33, v33, v41
	s_nop 1
	v_permlane16_swap_b32_e32 v26, v30
	v_permlane16_swap_b32_e32 v27, v31
	v_permlane16_swap_b32_e32 v28, v32
	v_permlane16_swap_b32_e32 v29, v33
	v_add_f32_e32 v26, v26, v30
	v_add_f32_e32 v27, v27, v31
	v_add_f32_e32 v28, v28, v32
	v_add_f32_e32 v29, v29, v33
	s_lshl_b32 s11, s12, 12
	v_add_u32_e32 v6, s11, v3
	v_add_f32_dpp v42, v26, v26 row_ror:8 row_mask:0xf bank_mask:0xf
	v_add_f32_dpp v43, v28, v28 row_ror:8 row_mask:0xf bank_mask:0xf
	v_add_f32_dpp v44, v27, v27 row_ror:8 row_mask:0xf bank_mask:0xf
	v_add_f32_dpp v45, v29, v29 row_ror:8 row_mask:0xf bank_mask:0xf
	v_cndmask_b32_e64 v46, v42, v43, s[14:15]
	v_cndmask_b32_e64 v47, v44, v45, s[14:15]
	v_add_f32_e32 v46, v56, v46
	v_add_f32_e32 v47, v57, v47
	global_store_dwordx2 v6, v[46:47], s[6:7]
	v_mul_f32_e32 v48, v46, v46
	v_fmac_f32_e32 v48, v47, v47
	s_lshl_b32 s11, s12, 2
	s_add_u32 s11, s11, 0x1100000
	v_mov_b32_e32 v7, s11
	v_add_f32_dpp v48, v48, v48 quad_perm:[1,0,3,2] row_mask:0xf bank_mask:0xf
	s_nop 1
	v_add_f32_dpp v48, v48, v48 quad_perm:[2,3,0,1] row_mask:0xf bank_mask:0xf
	s_nop 1
	v_add_f32_dpp v48, v48, v48 row_half_mirror row_mask:0xf bank_mask:0xf
	s_nop 1
	v_add_f32_dpp v48, v48, v48 row_mirror row_mask:0xf bank_mask:0xf
	s_nop 1
	v_add_f32_dpp v48, v48, v48 row_bcast:15 row_mask:0xa bank_mask:0xf
	s_nop 1
	v_add_f32_dpp v48, v48, v48 row_bcast:31 row_mask:0xc bank_mask:0xf
	s_nop 1
	s_mov_b32 exec_lo, 0
	s_brev_b32 exec_hi, 1
	global_atomic_add_f32 v7, v48, s[4:5]
	s_mov_b64 exec, -1
.Lp5v_skip3:
	s_add_u32 s8, s8, s23
	s_add_u32 s16, s16, 4
	s_cmp_lt_u32 s8, 0x4200
	s_cbranch_scc1 .Lp5v_loop
	s_waitcnt vmcnt(0)
